# re-measure: K-loop heads aligned 64B + stage-2 rewrite + rs hoist
# baseline (speedup 1.0000x reference)
.LBB0_142:
	s_ashr_i32 s13, s12, 31
	s_lshl_b64 s[16:17], s[12:13], 19
	s_add_u32 s13, s86, s16
	s_addc_u32 s15, s87, s17
	s_and_b64 s[16:17], s[0:1], exec
	s_cselect_b32 s17, s15, s23
	s_cselect_b32 s16, s13, s22
	s_ashr_i32 s15, s14, 31
	s_lshl_b64 s[18:19], s[14:15], 19
	v_readlane_b32 s28, v235, 22
	v_readlane_b32 s29, v235, 23
	s_add_u32 s13, s28, s18
	s_addc_u32 s15, s29, s19
	s_and_b64 s[18:19], s[0:1], exec
	s_cselect_b32 s19, s15, s27
	s_cselect_b32 s18, s13, s26
	s_cmp_lt_i32 s46, 1
	s_cbranch_scc1 .LBB0_150
	s_add_i32 s13, s46, -2
	s_add_u32 s22, s22, 0x40080
	s_addc_u32 s23, s23, 0
	s_add_u32 s15, s26, 0x100
	v_mov_b32_e32 v0, 0
	s_addc_u32 s47, s27, 0
	s_mov_b32 s26, 0
	v_mov_b32_e32 v1, v0
	v_mov_b32_e32 v2, v0
	v_mov_b32_e32 v3, v0
	v_mov_b32_e32 v4, v0
	v_mov_b32_e32 v5, v0
	v_mov_b32_e32 v6, v0
	v_mov_b32_e32 v7, v0
	v_mov_b32_e32 v16, v0
	v_mov_b32_e32 v17, v0
	v_mov_b32_e32 v18, v0
	v_mov_b32_e32 v19, v0
	v_mov_b32_e32 v20, v0
	v_mov_b32_e32 v21, v0
	v_mov_b32_e32 v22, v0
	v_mov_b32_e32 v23, v0
	v_mov_b32_e32 v32, v0
	v_mov_b32_e32 v33, v0
	v_mov_b32_e32 v34, v0
	v_mov_b32_e32 v35, v0
	v_mov_b32_e32 v36, v0
	v_mov_b32_e32 v37, v0
	v_mov_b32_e32 v38, v0
	v_mov_b32_e32 v39, v0
	v_mov_b32_e32 v48, v0
	v_mov_b32_e32 v49, v0
	v_mov_b32_e32 v50, v0
	v_mov_b32_e32 v51, v0
	v_mov_b32_e32 v52, v0
	v_mov_b32_e32 v53, v0
	v_mov_b32_e32 v54, v0
	v_mov_b32_e32 v55, v0
	v_mov_b32_e32 v8, v0
	v_mov_b32_e32 v9, v0
	v_mov_b32_e32 v10, v0
	v_mov_b32_e32 v11, v0
	v_mov_b32_e32 v12, v0
	v_mov_b32_e32 v13, v0
	v_mov_b32_e32 v14, v0
	v_mov_b32_e32 v15, v0
	v_mov_b32_e32 v24, v0
	v_mov_b32_e32 v25, v0
	v_mov_b32_e32 v26, v0
	v_mov_b32_e32 v27, v0
	v_mov_b32_e32 v28, v0
	v_mov_b32_e32 v29, v0
	v_mov_b32_e32 v30, v0
	v_mov_b32_e32 v31, v0
	v_mov_b32_e32 v40, v0
	v_mov_b32_e32 v41, v0
	v_mov_b32_e32 v42, v0
	v_mov_b32_e32 v43, v0
	v_mov_b32_e32 v44, v0
	v_mov_b32_e32 v45, v0
	v_mov_b32_e32 v46, v0
	v_mov_b32_e32 v47, v0
	v_mov_b32_e32 v56, v0
	v_mov_b32_e32 v57, v0
	v_mov_b32_e32 v58, v0
	v_mov_b32_e32 v59, v0
	v_mov_b32_e32 v60, v0
	v_mov_b32_e32 v61, v0
	v_mov_b32_e32 v62, v0
	v_mov_b32_e32 v63, v0
	v_mov_b32_e32 v64, v0
	v_mov_b32_e32 v65, v0
	v_mov_b32_e32 v66, v0
	v_mov_b32_e32 v67, v0
	v_mov_b32_e32 v68, v0
	v_mov_b32_e32 v69, v0
	v_mov_b32_e32 v70, v0
	v_mov_b32_e32 v71, v0
	v_mov_b32_e32 v80, v0
	v_mov_b32_e32 v81, v0
	v_mov_b32_e32 v82, v0
	v_mov_b32_e32 v83, v0
	v_mov_b32_e32 v84, v0
	v_mov_b32_e32 v85, v0
	v_mov_b32_e32 v86, v0
	v_mov_b32_e32 v87, v0
	v_mov_b32_e32 v96, v0
	v_mov_b32_e32 v97, v0
	v_mov_b32_e32 v98, v0
	v_mov_b32_e32 v99, v0
	v_mov_b32_e32 v100, v0
	v_mov_b32_e32 v101, v0
	v_mov_b32_e32 v102, v0
	v_mov_b32_e32 v103, v0
	v_mov_b32_e32 v112, v0
	v_mov_b32_e32 v113, v0
	v_mov_b32_e32 v114, v0
	v_mov_b32_e32 v115, v0
	v_mov_b32_e32 v116, v0
	v_mov_b32_e32 v117, v0
	v_mov_b32_e32 v118, v0
	v_mov_b32_e32 v119, v0
	v_mov_b32_e32 v72, v0
	v_mov_b32_e32 v73, v0
	v_mov_b32_e32 v74, v0
	v_mov_b32_e32 v75, v0
	v_mov_b32_e32 v76, v0
	v_mov_b32_e32 v77, v0
	v_mov_b32_e32 v78, v0
	v_mov_b32_e32 v79, v0
	v_mov_b32_e32 v88, v0
	v_mov_b32_e32 v89, v0
	v_mov_b32_e32 v90, v0
	v_mov_b32_e32 v91, v0
	v_mov_b32_e32 v92, v0
	v_mov_b32_e32 v93, v0
	v_mov_b32_e32 v94, v0
	v_mov_b32_e32 v95, v0
	v_mov_b32_e32 v104, v0
	v_mov_b32_e32 v105, v0
	v_mov_b32_e32 v106, v0
	v_mov_b32_e32 v107, v0
	v_mov_b32_e32 v108, v0
	v_mov_b32_e32 v109, v0
	v_mov_b32_e32 v110, v0
	v_mov_b32_e32 v111, v0
	v_mov_b32_e32 v120, v0
	v_mov_b32_e32 v121, v0
	v_mov_b32_e32 v122, v0
	v_mov_b32_e32 v123, v0
	v_mov_b32_e32 v124, v0
	v_mov_b32_e32 v125, v0
	v_mov_b32_e32 v126, v0
	v_mov_b32_e32 v127, v0
	.p2align 6

.LBB0_209:
	v_and_b32_e32 v14, 15, v140
	v_readlane_b32 s10, v235, 34
	v_and_b32_e32 v17, 48, v140
	v_ashrrev_i32_e32 v15, 6, v140
	v_or_b32_e32 v141, s10, v14
	v_lshlrev_b32_e32 v16, 6, v141
	s_movk_i32 s10, 0x3c0
	v_and_or_b32 v16, v16, s10, v17
	v_readlane_b32 s10, v235, 36
	s_add_i32 m0, s1, 0x18000
	s_waitcnt vmcnt(2)
	s_barrier
	v_lshl_add_u32 v18, v15, 10, s10
	v_readlane_b32 s10, v235, 38
	s_add_i32 s20, s1, 0x8000
	s_add_i32 s21, s1, 0xa000
	v_add_lshl_u32 v15, v15, s10, 10
	s_mov_b64 s[10:11], 0x80
	v_lshl_add_u64 v[6:7], v[6:7], 0, s[10:11]
	global_load_lds_dwordx4 v[6:7], off
	v_lshl_add_u64 v[4:5], v[4:5], 0, s[10:11]
	s_add_i32 m0, s1, 0x1a000
	v_lshl_add_u64 v[0:1], v[0:1], 0, s[10:11]
	global_load_lds_dwordx4 v[4:5], off
	s_mov_b32 m0, s20
	s_add_u32 s14, s6, 0x40080
	global_load_lds_dwordx4 v[0:1], off
	v_lshl_add_u64 v[0:1], v[2:3], 0, s[10:11]
	s_mov_b32 m0, s21
	s_addc_u32 s15, s7, 0
	global_load_lds_dwordx4 v[0:1], off
	s_add_i32 m0, s1, 0x1c000
	v_lshl_add_u64 v[0:1], s[14:15], 0, v[132:133]
	global_load_lds_dwordx4 v[0:1], off
	v_lshl_add_u64 v[0:1], s[14:15], 0, v[128:129]
	s_add_i32 m0, s1, 0x1e000
	s_ashr_i32 s13, s12, 31
	global_load_lds_dwordx4 v[0:1], off
	v_lshlrev_b32_e32 v0, 14, v11
	v_and_b32_e32 v0, 0xffff8000, v0
	s_lshl_b64 s[12:13], s[12:13], 19
	v_lshl_add_u32 v0, v12, 11, v0
	v_and_b32_e32 v1, 1, v11
	v_lshl_or_b32 v0, v1, 6, v0
	s_add_u32 s12, s78, s12
	v_lshl_add_u32 v0, v13, 1, v0
	v_mov_b32_e32 v1, v133
	s_addc_u32 s13, s79, s13
	v_lshl_add_u64 v[136:137], s[12:13], 0, v[0:1]
	v_lshlrev_b32_e32 v0, 14, v8
	v_lshl_or_b32 v14, v14, 6, v17
	v_lshlrev_b32_e32 v17, 2, v140
	v_and_b32_e32 v0, 0xffff8000, v0
	v_lshlrev_b32_e32 v19, 2, v141
	v_and_b32_e32 v17, 32, v17
	v_lshl_add_u32 v0, v9, 11, v0
	v_and_b32_e32 v1, 1, v8
	v_and_b32_e32 v19, 32, v19
	v_bitop3_b32 v14, v14, v15, v17 bitop3:0xde
	s_waitcnt vmcnt(6)
	v_lshl_or_b32 v0, v1, 6, v0
	s_add_i32 s27, 0, 0x10000
	s_add_i32 s29, 0, 0x14000
	s_add_i32 s31, 0, 0x18000
	s_add_i32 s35, 0, 0x1c000
	v_bitop3_b32 v16, v16, v18, v19 bitop3:0xde
	v_lshl_add_u32 v0, v10, 1, v0
	v_mov_b32_e32 v1, v133
	v_add_u32_e32 v142, s27, v14
	v_add_u32_e32 v143, s29, v14
	s_add_i32 s27, s27, s3
	s_add_i32 s29, s29, s3
	v_add_u32_e32 v145, s31, v14
	v_add_u32_e32 v146, s35, v14
	s_add_i32 s31, s31, s3
	s_add_i32 s35, s35, s3
	v_lshl_add_u64 v[138:139], s[12:13], 0, v[0:1]
	s_mov_b32 s22, -2
	s_mov_b64 s[12:13], 0x3840080
	v_add_u32_e32 v144, 0, v16
	s_add_i32 s23, s1, 0xc000
	s_add_i32 s26, s1, 0xe000
	s_add_i32 s28, s27, 0x2000
	s_add_i32 s30, s29, 0x2000
	s_add_i32 s34, s31, 0x2000
	s_add_i32 s36, s35, 0x2000
	v_mov_b32_e32 v0, v133
	v_mov_b32_e32 v2, v133
	v_mov_b32_e32 v3, v133
	v_mov_b32_e32 v4, v133
	v_mov_b32_e32 v5, v133
	v_mov_b32_e32 v6, v133
	v_mov_b32_e32 v7, v133
	v_mov_b32_e32 v16, v133
	v_mov_b32_e32 v17, v133
	v_mov_b32_e32 v18, v133
	v_mov_b32_e32 v19, v133
	v_mov_b32_e32 v20, v133
	v_mov_b32_e32 v21, v133
	v_mov_b32_e32 v22, v133
	v_mov_b32_e32 v23, v133
	v_mov_b32_e32 v32, v133
	v_mov_b32_e32 v33, v133
	v_mov_b32_e32 v34, v133
	v_mov_b32_e32 v35, v133
	v_mov_b32_e32 v36, v133
	v_mov_b32_e32 v37, v133
	v_mov_b32_e32 v38, v133
	v_mov_b32_e32 v39, v133
	v_mov_b32_e32 v48, v133
	v_mov_b32_e32 v49, v133
	v_mov_b32_e32 v50, v133
	v_mov_b32_e32 v51, v133
	v_mov_b32_e32 v52, v133
	v_mov_b32_e32 v53, v133
	v_mov_b32_e32 v54, v133
	v_mov_b32_e32 v55, v133
	v_mov_b32_e32 v8, v133
	v_mov_b32_e32 v9, v133
	v_mov_b32_e32 v10, v133
	v_mov_b32_e32 v11, v133
	v_mov_b32_e32 v12, v133
	v_mov_b32_e32 v13, v133
	v_mov_b32_e32 v14, v133
	v_mov_b32_e32 v15, v133
	v_mov_b32_e32 v24, v133
	v_mov_b32_e32 v25, v133
	v_mov_b32_e32 v26, v133
	v_mov_b32_e32 v27, v133
	v_mov_b32_e32 v28, v133
	v_mov_b32_e32 v29, v133
	v_mov_b32_e32 v30, v133
	v_mov_b32_e32 v31, v133
	v_mov_b32_e32 v40, v133
	v_mov_b32_e32 v41, v133
	v_mov_b32_e32 v42, v133
	v_mov_b32_e32 v43, v133
	v_mov_b32_e32 v44, v133
	v_mov_b32_e32 v45, v133
	v_mov_b32_e32 v46, v133
	v_mov_b32_e32 v47, v133
	v_mov_b32_e32 v56, v133
	v_mov_b32_e32 v57, v133
	v_mov_b32_e32 v58, v133
	v_mov_b32_e32 v59, v133
	v_mov_b32_e32 v60, v133
	v_mov_b32_e32 v61, v133
	v_mov_b32_e32 v62, v133
	v_mov_b32_e32 v63, v133
	v_mov_b32_e32 v64, v133
	v_mov_b32_e32 v65, v133
	v_mov_b32_e32 v66, v133
	v_mov_b32_e32 v67, v133
	v_mov_b32_e32 v68, v133
	v_mov_b32_e32 v69, v133
	v_mov_b32_e32 v70, v133
	v_mov_b32_e32 v71, v133
	v_mov_b32_e32 v72, v133
	v_mov_b32_e32 v73, v133
	v_mov_b32_e32 v74, v133
	v_mov_b32_e32 v75, v133
	v_mov_b32_e32 v80, v133
	v_mov_b32_e32 v81, v133
	v_mov_b32_e32 v82, v133
	v_mov_b32_e32 v83, v133
	v_mov_b32_e32 v96, v133
	v_mov_b32_e32 v97, v133
	v_mov_b32_e32 v98, v133
	v_mov_b32_e32 v99, v133
	v_mov_b32_e32 v100, v133
	v_mov_b32_e32 v101, v133
	v_mov_b32_e32 v102, v133
	v_mov_b32_e32 v103, v133
	v_mov_b32_e32 v112, v133
	v_mov_b32_e32 v113, v133
	v_mov_b32_e32 v114, v133
	v_mov_b32_e32 v115, v133
	v_mov_b32_e32 v116, v133
	v_mov_b32_e32 v117, v133
	v_mov_b32_e32 v118, v133
	v_mov_b32_e32 v119, v133
	v_mov_b32_e32 v76, v133
	v_mov_b32_e32 v77, v133
	v_mov_b32_e32 v78, v133
	v_mov_b32_e32 v79, v133
	v_mov_b32_e32 v84, v133
	v_mov_b32_e32 v85, v133
	v_mov_b32_e32 v86, v133
	v_mov_b32_e32 v87, v133
	v_mov_b32_e32 v88, v133
	v_mov_b32_e32 v89, v133
	v_mov_b32_e32 v90, v133
	v_mov_b32_e32 v91, v133
	v_mov_b32_e32 v92, v133
	v_mov_b32_e32 v93, v133
	v_mov_b32_e32 v94, v133
	v_mov_b32_e32 v95, v133
	v_mov_b32_e32 v104, v133
	v_mov_b32_e32 v105, v133
	v_mov_b32_e32 v106, v133
	v_mov_b32_e32 v107, v133
	v_mov_b32_e32 v108, v133
	v_mov_b32_e32 v109, v133
	v_mov_b32_e32 v110, v133
	v_mov_b32_e32 v111, v133
	v_mov_b32_e32 v120, v133
	v_mov_b32_e32 v121, v133
	v_mov_b32_e32 v122, v133
	v_mov_b32_e32 v123, v133
	v_mov_b32_e32 v124, v133
	v_mov_b32_e32 v125, v133
	v_mov_b32_e32 v126, v133
	v_mov_b32_e32 v127, v133
	s_barrier
	.p2align 6

.LBB0_380:
	s_add_i32 s17, s1, -2
	s_add_u32 s28, s28, 0x40080
	s_addc_u32 s29, s29, 0
	s_add_u32 s19, s34, 0x100
	v_mov_b32_e32 v0, 0
	s_addc_u32 s21, s35, 0
	s_mov_b32 s23, 0
	v_mov_b32_e32 v1, v0
	v_mov_b32_e32 v2, v0
	v_mov_b32_e32 v3, v0
	v_mov_b32_e32 v4, v0
	v_mov_b32_e32 v5, v0
	v_mov_b32_e32 v6, v0
	v_mov_b32_e32 v7, v0
	v_mov_b32_e32 v8, v0
	v_mov_b32_e32 v9, v0
	v_mov_b32_e32 v10, v0
	v_mov_b32_e32 v11, v0
	v_mov_b32_e32 v12, v0
	v_mov_b32_e32 v13, v0
	v_mov_b32_e32 v14, v0
	v_mov_b32_e32 v15, v0
	v_mov_b32_e32 v24, v0
	v_mov_b32_e32 v25, v0
	v_mov_b32_e32 v26, v0
	v_mov_b32_e32 v27, v0
	v_mov_b32_e32 v28, v0
	v_mov_b32_e32 v29, v0
	v_mov_b32_e32 v30, v0
	v_mov_b32_e32 v31, v0
	v_mov_b32_e32 v40, v0
	v_mov_b32_e32 v41, v0
	v_mov_b32_e32 v42, v0
	v_mov_b32_e32 v43, v0
	v_mov_b32_e32 v44, v0
	v_mov_b32_e32 v45, v0
	v_mov_b32_e32 v46, v0
	v_mov_b32_e32 v47, v0
	v_mov_b32_e32 v16, v0
	v_mov_b32_e32 v17, v0
	v_mov_b32_e32 v18, v0
	v_mov_b32_e32 v19, v0
	v_mov_b32_e32 v20, v0
	v_mov_b32_e32 v21, v0
	v_mov_b32_e32 v22, v0
	v_mov_b32_e32 v23, v0
	v_mov_b32_e32 v32, v0
	v_mov_b32_e32 v33, v0
	v_mov_b32_e32 v34, v0
	v_mov_b32_e32 v35, v0
	v_mov_b32_e32 v36, v0
	v_mov_b32_e32 v37, v0
	v_mov_b32_e32 v38, v0
	v_mov_b32_e32 v39, v0
	v_mov_b32_e32 v48, v0
	v_mov_b32_e32 v49, v0
	v_mov_b32_e32 v50, v0
	v_mov_b32_e32 v51, v0
	v_mov_b32_e32 v52, v0
	v_mov_b32_e32 v53, v0
	v_mov_b32_e32 v54, v0
	v_mov_b32_e32 v55, v0
	v_mov_b32_e32 v56, v0
	v_mov_b32_e32 v57, v0
	v_mov_b32_e32 v58, v0
	v_mov_b32_e32 v59, v0
	v_mov_b32_e32 v60, v0
	v_mov_b32_e32 v61, v0
	v_mov_b32_e32 v62, v0
	v_mov_b32_e32 v63, v0
	v_mov_b32_e32 v64, v0
	v_mov_b32_e32 v65, v0
	v_mov_b32_e32 v66, v0
	v_mov_b32_e32 v67, v0
	v_mov_b32_e32 v68, v0
	v_mov_b32_e32 v69, v0
	v_mov_b32_e32 v70, v0
	v_mov_b32_e32 v71, v0
	v_mov_b32_e32 v72, v0
	v_mov_b32_e32 v73, v0
	v_mov_b32_e32 v74, v0
	v_mov_b32_e32 v75, v0
	v_mov_b32_e32 v76, v0
	v_mov_b32_e32 v77, v0
	v_mov_b32_e32 v78, v0
	v_mov_b32_e32 v79, v0
	v_mov_b32_e32 v88, v0
	v_mov_b32_e32 v89, v0
	v_mov_b32_e32 v90, v0
	v_mov_b32_e32 v91, v0
	v_mov_b32_e32 v92, v0
	v_mov_b32_e32 v93, v0
	v_mov_b32_e32 v94, v0
	v_mov_b32_e32 v95, v0
	v_mov_b32_e32 v104, v0
	v_mov_b32_e32 v105, v0
	v_mov_b32_e32 v106, v0
	v_mov_b32_e32 v107, v0
	v_mov_b32_e32 v108, v0
	v_mov_b32_e32 v109, v0
	v_mov_b32_e32 v110, v0
	v_mov_b32_e32 v111, v0
	v_mov_b32_e32 v80, v0
	v_mov_b32_e32 v81, v0
	v_mov_b32_e32 v82, v0
	v_mov_b32_e32 v83, v0
	v_mov_b32_e32 v84, v0
	v_mov_b32_e32 v85, v0
	v_mov_b32_e32 v86, v0
	v_mov_b32_e32 v87, v0
	v_mov_b32_e32 v96, v0
	v_mov_b32_e32 v97, v0
	v_mov_b32_e32 v98, v0
	v_mov_b32_e32 v99, v0
	v_mov_b32_e32 v100, v0
	v_mov_b32_e32 v101, v0
	v_mov_b32_e32 v102, v0
	v_mov_b32_e32 v103, v0
	v_mov_b32_e32 v112, v0
	v_mov_b32_e32 v113, v0
	v_mov_b32_e32 v114, v0
	v_mov_b32_e32 v115, v0
	v_mov_b32_e32 v116, v0
	v_mov_b32_e32 v117, v0
	v_mov_b32_e32 v118, v0
	v_mov_b32_e32 v119, v0
	v_mov_b32_e32 v120, v0
	v_mov_b32_e32 v121, v0
	v_mov_b32_e32 v122, v0
	v_mov_b32_e32 v123, v0
	v_mov_b32_e32 v124, v0
	v_mov_b32_e32 v125, v0
	v_mov_b32_e32 v126, v0
	v_mov_b32_e32 v127, v0
	.p2align 6

.LBB0_534:
	s_ashr_i32 s1, s0, 31
	s_lshl_b64 s[30:31], s[0:1], 19
	s_add_u32 s90, s86, s30
	s_addc_u32 s91, s87, s31
	s_and_b64 s[30:31], s[6:7], exec
	s_cselect_b32 s1, s91, s21
	s_cselect_b32 s11, s90, s20
	s_ashr_i32 s83, s82, 31
	s_lshl_b64 s[30:31], s[82:83], 19
	v_readlane_b32 s36, v235, 26
	v_readlane_b32 s37, v235, 27
	s_add_u32 s36, s36, s30
	s_addc_u32 s37, s37, s31
	s_and_b64 s[30:31], s[6:7], exec
	s_cselect_b32 s13, s37, s23
	s_cselect_b32 s30, s36, s22
	s_add_u32 s31, s22, 0x100
	v_mov_b32_e32 v4, 0
	s_addc_u32 s83, s23, 0
	s_mov_b32 s86, -2
	v_mov_b32_e32 v5, v4
	v_mov_b32_e32 v6, v4
	v_mov_b32_e32 v7, v4
	v_mov_b32_e32 v0, v4
	v_mov_b32_e32 v1, v4
	v_mov_b32_e32 v2, v4
	v_mov_b32_e32 v3, v4
	v_mov_b32_e32 v28, v4
	v_mov_b32_e32 v29, v4
	v_mov_b32_e32 v30, v4
	v_mov_b32_e32 v31, v4
	v_mov_b32_e32 v20, v4
	v_mov_b32_e32 v21, v4
	v_mov_b32_e32 v22, v4
	v_mov_b32_e32 v23, v4
	v_mov_b32_e32 v24, v4
	v_mov_b32_e32 v25, v4
	v_mov_b32_e32 v26, v4
	v_mov_b32_e32 v27, v4
	v_mov_b32_e32 v32, v4
	v_mov_b32_e32 v33, v4
	v_mov_b32_e32 v34, v4
	v_mov_b32_e32 v35, v4
	v_mov_b32_e32 v44, v4
	v_mov_b32_e32 v45, v4
	v_mov_b32_e32 v46, v4
	v_mov_b32_e32 v47, v4
	v_mov_b32_e32 v40, v4
	v_mov_b32_e32 v41, v4
	v_mov_b32_e32 v42, v4
	v_mov_b32_e32 v43, v4
	v_mov_b32_e32 v12, v4
	v_mov_b32_e32 v13, v4
	v_mov_b32_e32 v14, v4
	v_mov_b32_e32 v15, v4
	v_mov_b32_e32 v8, v4
	v_mov_b32_e32 v9, v4
	v_mov_b32_e32 v10, v4
	v_mov_b32_e32 v11, v4
	v_mov_b32_e32 v128, v4
	v_mov_b32_e32 v129, v4
	v_mov_b32_e32 v130, v4
	v_mov_b32_e32 v131, v4
	v_mov_b32_e32 v132, v4
	v_mov_b32_e32 v133, v4
	v_mov_b32_e32 v134, v4
	v_mov_b32_e32 v135, v4
	v_mov_b32_e32 v48, v4
	v_mov_b32_e32 v49, v4
	v_mov_b32_e32 v50, v4
	v_mov_b32_e32 v51, v4
	v_mov_b32_e32 v52, v4
	v_mov_b32_e32 v53, v4
	v_mov_b32_e32 v54, v4
	v_mov_b32_e32 v55, v4
	v_mov_b32_e32 v36, v4
	v_mov_b32_e32 v37, v4
	v_mov_b32_e32 v38, v4
	v_mov_b32_e32 v39, v4
	v_mov_b32_e32 v16, v4
	v_mov_b32_e32 v17, v4
	v_mov_b32_e32 v18, v4
	v_mov_b32_e32 v19, v4
	v_mov_b32_e32 v56, v4
	v_mov_b32_e32 v57, v4
	v_mov_b32_e32 v58, v4
	v_mov_b32_e32 v59, v4
	v_mov_b32_e32 v60, v4
	v_mov_b32_e32 v61, v4
	v_mov_b32_e32 v62, v4
	v_mov_b32_e32 v63, v4
	v_mov_b32_e32 v64, v4
	v_mov_b32_e32 v65, v4
	v_mov_b32_e32 v66, v4
	v_mov_b32_e32 v67, v4
	v_mov_b32_e32 v68, v4
	v_mov_b32_e32 v69, v4
	v_mov_b32_e32 v70, v4
	v_mov_b32_e32 v71, v4
	v_mov_b32_e32 v72, v4
	v_mov_b32_e32 v73, v4
	v_mov_b32_e32 v74, v4
	v_mov_b32_e32 v75, v4
	v_mov_b32_e32 v76, v4
	v_mov_b32_e32 v77, v4
	v_mov_b32_e32 v78, v4
	v_mov_b32_e32 v79, v4
	v_mov_b32_e32 v80, v4
	v_mov_b32_e32 v81, v4
	v_mov_b32_e32 v82, v4
	v_mov_b32_e32 v83, v4
	v_mov_b32_e32 v88, v4
	v_mov_b32_e32 v89, v4
	v_mov_b32_e32 v90, v4
	v_mov_b32_e32 v91, v4
	v_mov_b32_e32 v136, v4
	v_mov_b32_e32 v137, v4
	v_mov_b32_e32 v138, v4
	v_mov_b32_e32 v139, v4
	v_mov_b32_e32 v140, v4
	v_mov_b32_e32 v141, v4
	v_mov_b32_e32 v142, v4
	v_mov_b32_e32 v143, v4
	v_mov_b32_e32 v84, v4
	v_mov_b32_e32 v85, v4
	v_mov_b32_e32 v86, v4
	v_mov_b32_e32 v87, v4
	v_mov_b32_e32 v92, v4
	v_mov_b32_e32 v93, v4
	v_mov_b32_e32 v94, v4
	v_mov_b32_e32 v95, v4
	v_mov_b32_e32 v116, v4
	v_mov_b32_e32 v117, v4
	v_mov_b32_e32 v118, v4
	v_mov_b32_e32 v119, v4
	v_mov_b32_e32 v112, v4
	v_mov_b32_e32 v113, v4
	v_mov_b32_e32 v114, v4
	v_mov_b32_e32 v115, v4
	v_mov_b32_e32 v100, v4
	v_mov_b32_e32 v101, v4
	v_mov_b32_e32 v102, v4
	v_mov_b32_e32 v103, v4
	v_mov_b32_e32 v96, v4
	v_mov_b32_e32 v97, v4
	v_mov_b32_e32 v98, v4
	v_mov_b32_e32 v99, v4
	.p2align 6

.LBB0_655:
	s_add_i32 s15, s44, -2
	s_add_u32 s45, s20, 0x100
	v_mov_b32_e32 v0, 0
	s_addc_u32 s46, s21, 0
	s_mov_b32 s22, 0
	v_mov_b32_e32 v1, v0
	v_mov_b32_e32 v2, v0
	v_mov_b32_e32 v3, v0
	v_mov_b32_e32 v4, v0
	v_mov_b32_e32 v5, v0
	v_mov_b32_e32 v6, v0
	v_mov_b32_e32 v7, v0
	v_mov_b32_e32 v8, v0
	v_mov_b32_e32 v9, v0
	v_mov_b32_e32 v10, v0
	v_mov_b32_e32 v11, v0
	v_mov_b32_e32 v12, v0
	v_mov_b32_e32 v13, v0
	v_mov_b32_e32 v14, v0
	v_mov_b32_e32 v15, v0
	v_mov_b32_e32 v24, v0
	v_mov_b32_e32 v25, v0
	v_mov_b32_e32 v26, v0
	v_mov_b32_e32 v27, v0
	v_mov_b32_e32 v28, v0
	v_mov_b32_e32 v29, v0
	v_mov_b32_e32 v30, v0
	v_mov_b32_e32 v31, v0
	v_mov_b32_e32 v40, v0
	v_mov_b32_e32 v41, v0
	v_mov_b32_e32 v42, v0
	v_mov_b32_e32 v43, v0
	v_mov_b32_e32 v44, v0
	v_mov_b32_e32 v45, v0
	v_mov_b32_e32 v46, v0
	v_mov_b32_e32 v47, v0
	v_mov_b32_e32 v16, v0
	v_mov_b32_e32 v17, v0
	v_mov_b32_e32 v18, v0
	v_mov_b32_e32 v19, v0
	v_mov_b32_e32 v20, v0
	v_mov_b32_e32 v21, v0
	v_mov_b32_e32 v22, v0
	v_mov_b32_e32 v23, v0
	v_mov_b32_e32 v32, v0
	v_mov_b32_e32 v33, v0
	v_mov_b32_e32 v34, v0
	v_mov_b32_e32 v35, v0
	v_mov_b32_e32 v36, v0
	v_mov_b32_e32 v37, v0
	v_mov_b32_e32 v38, v0
	v_mov_b32_e32 v39, v0
	v_mov_b32_e32 v48, v0
	v_mov_b32_e32 v49, v0
	v_mov_b32_e32 v50, v0
	v_mov_b32_e32 v51, v0
	v_mov_b32_e32 v52, v0
	v_mov_b32_e32 v53, v0
	v_mov_b32_e32 v54, v0
	v_mov_b32_e32 v55, v0
	v_mov_b32_e32 v56, v0
	v_mov_b32_e32 v57, v0
	v_mov_b32_e32 v58, v0
	v_mov_b32_e32 v59, v0
	v_mov_b32_e32 v60, v0
	v_mov_b32_e32 v61, v0
	v_mov_b32_e32 v62, v0
	v_mov_b32_e32 v63, v0
	v_mov_b32_e32 v64, v0
	v_mov_b32_e32 v65, v0
	v_mov_b32_e32 v66, v0
	v_mov_b32_e32 v67, v0
	v_mov_b32_e32 v68, v0
	v_mov_b32_e32 v69, v0
	v_mov_b32_e32 v70, v0
	v_mov_b32_e32 v71, v0
	v_mov_b32_e32 v72, v0
	v_mov_b32_e32 v73, v0
	v_mov_b32_e32 v74, v0
	v_mov_b32_e32 v75, v0
	v_mov_b32_e32 v76, v0
	v_mov_b32_e32 v77, v0
	v_mov_b32_e32 v78, v0
	v_mov_b32_e32 v79, v0
	v_mov_b32_e32 v88, v0
	v_mov_b32_e32 v89, v0
	v_mov_b32_e32 v90, v0
	v_mov_b32_e32 v91, v0
	v_mov_b32_e32 v92, v0
	v_mov_b32_e32 v93, v0
	v_mov_b32_e32 v94, v0
	v_mov_b32_e32 v95, v0
	v_mov_b32_e32 v104, v0
	v_mov_b32_e32 v105, v0
	v_mov_b32_e32 v106, v0
	v_mov_b32_e32 v107, v0
	v_mov_b32_e32 v108, v0
	v_mov_b32_e32 v109, v0
	v_mov_b32_e32 v110, v0
	v_mov_b32_e32 v111, v0
	v_mov_b32_e32 v80, v0
	v_mov_b32_e32 v81, v0
	v_mov_b32_e32 v82, v0
	v_mov_b32_e32 v83, v0
	v_mov_b32_e32 v84, v0
	v_mov_b32_e32 v85, v0
	v_mov_b32_e32 v86, v0
	v_mov_b32_e32 v87, v0
	v_mov_b32_e32 v96, v0
	v_mov_b32_e32 v97, v0
	v_mov_b32_e32 v98, v0
	v_mov_b32_e32 v99, v0
	v_mov_b32_e32 v100, v0
	v_mov_b32_e32 v101, v0
	v_mov_b32_e32 v102, v0
	v_mov_b32_e32 v103, v0
	v_mov_b32_e32 v112, v0
	v_mov_b32_e32 v113, v0
	v_mov_b32_e32 v114, v0
	v_mov_b32_e32 v115, v0
	v_mov_b32_e32 v116, v0
	v_mov_b32_e32 v117, v0
	v_mov_b32_e32 v118, v0
	v_mov_b32_e32 v119, v0
	v_mov_b32_e32 v120, v0
	v_mov_b32_e32 v121, v0
	v_mov_b32_e32 v122, v0
	v_mov_b32_e32 v123, v0
	v_mov_b32_e32 v124, v0
	v_mov_b32_e32 v125, v0
	v_mov_b32_e32 v126, v0
	v_mov_b32_e32 v127, v0
	.p2align 6

.LBB0_851:
	s_ashr_i32 s11, s10, 31
	s_lshl_b64 s[14:15], s[10:11], 19
	s_add_u32 s11, s86, s14
	s_addc_u32 s13, s87, s15
	s_and_b64 s[14:15], s[8:9], exec
	s_cselect_b32 s15, s13, s21
	s_cselect_b32 s14, s11, s20
	s_ashr_i32 s13, s12, 31
	s_lshl_b64 s[16:17], s[12:13], 19
	v_readlane_b32 s24, v235, 22
	v_readlane_b32 s25, v235, 23
	s_add_u32 s11, s24, s16
	s_addc_u32 s13, s25, s17
	s_and_b64 s[16:17], s[8:9], exec
	s_cselect_b32 s17, s13, s23
	s_cselect_b32 s16, s11, s22
	s_cmp_lt_i32 s41, 1
	s_cbranch_scc1 .LBB0_859
	s_add_i32 s11, s41, -2
	s_add_u32 s20, s20, 0x40080
	s_addc_u32 s21, s21, 0
	s_add_u32 s13, s22, 0x100
	v_mov_b32_e32 v0, 0
	s_addc_u32 s42, s23, 0
	s_mov_b32 s22, 0
	v_mov_b32_e32 v1, v0
	v_mov_b32_e32 v2, v0
	v_mov_b32_e32 v3, v0
	v_mov_b32_e32 v4, v0
	v_mov_b32_e32 v5, v0
	v_mov_b32_e32 v6, v0
	v_mov_b32_e32 v7, v0
	v_mov_b32_e32 v16, v0
	v_mov_b32_e32 v17, v0
	v_mov_b32_e32 v18, v0
	v_mov_b32_e32 v19, v0
	v_mov_b32_e32 v20, v0
	v_mov_b32_e32 v21, v0
	v_mov_b32_e32 v22, v0
	v_mov_b32_e32 v23, v0
	v_mov_b32_e32 v32, v0
	v_mov_b32_e32 v33, v0
	v_mov_b32_e32 v34, v0
	v_mov_b32_e32 v35, v0
	v_mov_b32_e32 v36, v0
	v_mov_b32_e32 v37, v0
	v_mov_b32_e32 v38, v0
	v_mov_b32_e32 v39, v0
	v_mov_b32_e32 v48, v0
	v_mov_b32_e32 v49, v0
	v_mov_b32_e32 v50, v0
	v_mov_b32_e32 v51, v0
	v_mov_b32_e32 v52, v0
	v_mov_b32_e32 v53, v0
	v_mov_b32_e32 v54, v0
	v_mov_b32_e32 v55, v0
	v_mov_b32_e32 v8, v0
	v_mov_b32_e32 v9, v0
	v_mov_b32_e32 v10, v0
	v_mov_b32_e32 v11, v0
	v_mov_b32_e32 v12, v0
	v_mov_b32_e32 v13, v0
	v_mov_b32_e32 v14, v0
	v_mov_b32_e32 v15, v0
	v_mov_b32_e32 v24, v0
	v_mov_b32_e32 v25, v0
	v_mov_b32_e32 v26, v0
	v_mov_b32_e32 v27, v0
	v_mov_b32_e32 v28, v0
	v_mov_b32_e32 v29, v0
	v_mov_b32_e32 v30, v0
	v_mov_b32_e32 v31, v0
	v_mov_b32_e32 v40, v0
	v_mov_b32_e32 v41, v0
	v_mov_b32_e32 v42, v0
	v_mov_b32_e32 v43, v0
	v_mov_b32_e32 v44, v0
	v_mov_b32_e32 v45, v0
	v_mov_b32_e32 v46, v0
	v_mov_b32_e32 v47, v0
	v_mov_b32_e32 v56, v0
	v_mov_b32_e32 v57, v0
	v_mov_b32_e32 v58, v0
	v_mov_b32_e32 v59, v0
	v_mov_b32_e32 v60, v0
	v_mov_b32_e32 v61, v0
	v_mov_b32_e32 v62, v0
	v_mov_b32_e32 v63, v0
	v_mov_b32_e32 v64, v0
	v_mov_b32_e32 v65, v0
	v_mov_b32_e32 v66, v0
	v_mov_b32_e32 v67, v0
	v_mov_b32_e32 v68, v0
	v_mov_b32_e32 v69, v0
	v_mov_b32_e32 v70, v0
	v_mov_b32_e32 v71, v0
	v_mov_b32_e32 v80, v0
	v_mov_b32_e32 v81, v0
	v_mov_b32_e32 v82, v0
	v_mov_b32_e32 v83, v0
	v_mov_b32_e32 v84, v0
	v_mov_b32_e32 v85, v0
	v_mov_b32_e32 v86, v0
	v_mov_b32_e32 v87, v0
	v_mov_b32_e32 v96, v0
	v_mov_b32_e32 v97, v0
	v_mov_b32_e32 v98, v0
	v_mov_b32_e32 v99, v0
	v_mov_b32_e32 v100, v0
	v_mov_b32_e32 v101, v0
	v_mov_b32_e32 v102, v0
	v_mov_b32_e32 v103, v0
	v_mov_b32_e32 v112, v0
	v_mov_b32_e32 v113, v0
	v_mov_b32_e32 v114, v0
	v_mov_b32_e32 v115, v0
	v_mov_b32_e32 v116, v0
	v_mov_b32_e32 v117, v0
	v_mov_b32_e32 v118, v0
	v_mov_b32_e32 v119, v0
	v_mov_b32_e32 v72, v0
	v_mov_b32_e32 v73, v0
	v_mov_b32_e32 v74, v0
	v_mov_b32_e32 v75, v0
	v_mov_b32_e32 v76, v0
	v_mov_b32_e32 v77, v0
	v_mov_b32_e32 v78, v0
	v_mov_b32_e32 v79, v0
	v_mov_b32_e32 v88, v0
	v_mov_b32_e32 v89, v0
	v_mov_b32_e32 v90, v0
	v_mov_b32_e32 v91, v0
	v_mov_b32_e32 v92, v0
	v_mov_b32_e32 v93, v0
	v_mov_b32_e32 v94, v0
	v_mov_b32_e32 v95, v0
	v_mov_b32_e32 v104, v0
	v_mov_b32_e32 v105, v0
	v_mov_b32_e32 v106, v0
	v_mov_b32_e32 v107, v0
	v_mov_b32_e32 v108, v0
	v_mov_b32_e32 v109, v0
	v_mov_b32_e32 v110, v0
	v_mov_b32_e32 v111, v0
	v_mov_b32_e32 v120, v0
	v_mov_b32_e32 v121, v0
	v_mov_b32_e32 v122, v0
	v_mov_b32_e32 v123, v0
	v_mov_b32_e32 v124, v0
	v_mov_b32_e32 v125, v0
	v_mov_b32_e32 v126, v0
	v_mov_b32_e32 v127, v0
	.p2align 6

.LBB0_918:
	v_and_b32_e32 v14, 15, v140
	v_readlane_b32 s10, v235, 34
	v_and_b32_e32 v17, 48, v140
	v_ashrrev_i32_e32 v15, 6, v140
	v_or_b32_e32 v141, s10, v14
	v_lshlrev_b32_e32 v16, 6, v141
	s_movk_i32 s10, 0x3c0
	v_and_or_b32 v16, v16, s10, v17
	v_readlane_b32 s10, v235, 36
	s_add_i32 m0, s1, 0x18000
	s_waitcnt vmcnt(2)
	s_barrier
	v_lshl_add_u32 v18, v15, 10, s10
	v_readlane_b32 s10, v235, 38
	s_add_i32 s20, s1, 0x8000
	s_add_i32 s21, s1, 0xa000
	v_add_lshl_u32 v15, v15, s10, 10
	s_mov_b64 s[10:11], 0x80
	v_lshl_add_u64 v[6:7], v[6:7], 0, s[10:11]
	global_load_lds_dwordx4 v[6:7], off
	v_lshl_add_u64 v[4:5], v[4:5], 0, s[10:11]
	s_add_i32 m0, s1, 0x1a000
	v_lshl_add_u64 v[0:1], v[0:1], 0, s[10:11]
	global_load_lds_dwordx4 v[4:5], off
	s_mov_b32 m0, s20
	s_add_u32 s14, s6, 0x40080
	global_load_lds_dwordx4 v[0:1], off
	v_lshl_add_u64 v[0:1], v[2:3], 0, s[10:11]
	s_mov_b32 m0, s21
	s_addc_u32 s15, s7, 0
	global_load_lds_dwordx4 v[0:1], off
	s_add_i32 m0, s1, 0x1c000
	v_lshl_add_u64 v[0:1], s[14:15], 0, v[132:133]
	global_load_lds_dwordx4 v[0:1], off
	v_lshl_add_u64 v[0:1], s[14:15], 0, v[128:129]
	s_add_i32 m0, s1, 0x1e000
	s_ashr_i32 s13, s12, 31
	global_load_lds_dwordx4 v[0:1], off
	v_lshlrev_b32_e32 v0, 14, v11
	v_and_b32_e32 v0, 0xffff8000, v0
	s_lshl_b64 s[12:13], s[12:13], 19
	v_lshl_add_u32 v0, v12, 11, v0
	v_and_b32_e32 v1, 1, v11
	v_lshl_or_b32 v0, v1, 6, v0
	s_add_u32 s12, s78, s12
	v_lshl_add_u32 v0, v13, 1, v0
	v_mov_b32_e32 v1, v133
	s_addc_u32 s13, s79, s13
	v_lshl_add_u64 v[136:137], s[12:13], 0, v[0:1]
	v_lshlrev_b32_e32 v0, 14, v8
	v_lshl_or_b32 v14, v14, 6, v17
	v_lshlrev_b32_e32 v17, 2, v140
	v_and_b32_e32 v0, 0xffff8000, v0
	v_lshlrev_b32_e32 v19, 2, v141
	v_and_b32_e32 v17, 32, v17
	v_lshl_add_u32 v0, v9, 11, v0
	v_and_b32_e32 v1, 1, v8
	v_and_b32_e32 v19, 32, v19
	v_bitop3_b32 v14, v14, v15, v17 bitop3:0xde
	s_waitcnt vmcnt(6)
	v_lshl_or_b32 v0, v1, 6, v0
	s_add_i32 s25, 0, 0x10000
	s_add_i32 s27, 0, 0x14000
	s_add_i32 s29, 0, 0x18000
	s_add_i32 s31, 0, 0x1c000
	v_bitop3_b32 v16, v16, v18, v19 bitop3:0xde
	v_lshl_add_u32 v0, v10, 1, v0
	v_mov_b32_e32 v1, v133
	v_add_u32_e32 v142, s25, v14
	v_add_u32_e32 v143, s27, v14
	s_add_i32 s25, s25, s3
	s_add_i32 s27, s27, s3
	v_add_u32_e32 v145, s29, v14
	v_add_u32_e32 v146, s31, v14
	s_add_i32 s29, s29, s3
	s_add_i32 s31, s31, s3
	v_lshl_add_u64 v[138:139], s[12:13], 0, v[0:1]
	s_mov_b32 s22, -2
	s_mov_b64 s[12:13], 0x3840080
	v_add_u32_e32 v144, 0, v16
	s_add_i32 s23, s1, 0xc000
	s_add_i32 s24, s1, 0xe000
	s_add_i32 s26, s25, 0x2000
	s_add_i32 s28, s27, 0x2000
	s_add_i32 s30, s29, 0x2000
	s_add_i32 s36, s31, 0x2000
	v_mov_b32_e32 v0, v133
	v_mov_b32_e32 v2, v133
	v_mov_b32_e32 v3, v133
	v_mov_b32_e32 v4, v133
	v_mov_b32_e32 v5, v133
	v_mov_b32_e32 v6, v133
	v_mov_b32_e32 v7, v133
	v_mov_b32_e32 v16, v133
	v_mov_b32_e32 v17, v133
	v_mov_b32_e32 v18, v133
	v_mov_b32_e32 v19, v133
	v_mov_b32_e32 v20, v133
	v_mov_b32_e32 v21, v133
	v_mov_b32_e32 v22, v133
	v_mov_b32_e32 v23, v133
	v_mov_b32_e32 v32, v133
	v_mov_b32_e32 v33, v133
	v_mov_b32_e32 v34, v133
	v_mov_b32_e32 v35, v133
	v_mov_b32_e32 v36, v133
	v_mov_b32_e32 v37, v133
	v_mov_b32_e32 v38, v133
	v_mov_b32_e32 v39, v133
	v_mov_b32_e32 v48, v133
	v_mov_b32_e32 v49, v133
	v_mov_b32_e32 v50, v133
	v_mov_b32_e32 v51, v133
	v_mov_b32_e32 v52, v133
	v_mov_b32_e32 v53, v133
	v_mov_b32_e32 v54, v133
	v_mov_b32_e32 v55, v133
	v_mov_b32_e32 v8, v133
	v_mov_b32_e32 v9, v133
	v_mov_b32_e32 v10, v133
	v_mov_b32_e32 v11, v133
	v_mov_b32_e32 v12, v133
	v_mov_b32_e32 v13, v133
	v_mov_b32_e32 v14, v133
	v_mov_b32_e32 v15, v133
	v_mov_b32_e32 v24, v133
	v_mov_b32_e32 v25, v133
	v_mov_b32_e32 v26, v133
	v_mov_b32_e32 v27, v133
	v_mov_b32_e32 v28, v133
	v_mov_b32_e32 v29, v133
	v_mov_b32_e32 v30, v133
	v_mov_b32_e32 v31, v133
	v_mov_b32_e32 v40, v133
	v_mov_b32_e32 v41, v133
	v_mov_b32_e32 v42, v133
	v_mov_b32_e32 v43, v133
	v_mov_b32_e32 v44, v133
	v_mov_b32_e32 v45, v133
	v_mov_b32_e32 v46, v133
	v_mov_b32_e32 v47, v133
	v_mov_b32_e32 v56, v133
	v_mov_b32_e32 v57, v133
	v_mov_b32_e32 v58, v133
	v_mov_b32_e32 v59, v133
	v_mov_b32_e32 v60, v133
	v_mov_b32_e32 v61, v133
	v_mov_b32_e32 v62, v133
	v_mov_b32_e32 v63, v133
	v_mov_b32_e32 v64, v133
	v_mov_b32_e32 v65, v133
	v_mov_b32_e32 v66, v133
	v_mov_b32_e32 v67, v133
	v_mov_b32_e32 v68, v133
	v_mov_b32_e32 v69, v133
	v_mov_b32_e32 v70, v133
	v_mov_b32_e32 v71, v133
	v_mov_b32_e32 v80, v133
	v_mov_b32_e32 v81, v133
	v_mov_b32_e32 v82, v133
	v_mov_b32_e32 v83, v133
	v_mov_b32_e32 v84, v133
	v_mov_b32_e32 v85, v133
	v_mov_b32_e32 v86, v133
	v_mov_b32_e32 v87, v133
	v_mov_b32_e32 v96, v133
	v_mov_b32_e32 v97, v133
	v_mov_b32_e32 v98, v133
	v_mov_b32_e32 v99, v133
	v_mov_b32_e32 v100, v133
	v_mov_b32_e32 v101, v133
	v_mov_b32_e32 v102, v133
	v_mov_b32_e32 v103, v133
	v_mov_b32_e32 v112, v133
	v_mov_b32_e32 v113, v133
	v_mov_b32_e32 v114, v133
	v_mov_b32_e32 v115, v133
	v_mov_b32_e32 v116, v133
	v_mov_b32_e32 v117, v133
	v_mov_b32_e32 v118, v133
	v_mov_b32_e32 v119, v133
	v_mov_b32_e32 v72, v133
	v_mov_b32_e32 v73, v133
	v_mov_b32_e32 v74, v133
	v_mov_b32_e32 v75, v133
	v_mov_b32_e32 v76, v133
	v_mov_b32_e32 v77, v133
	v_mov_b32_e32 v78, v133
	v_mov_b32_e32 v79, v133
	v_mov_b32_e32 v88, v133
	v_mov_b32_e32 v89, v133
	v_mov_b32_e32 v90, v133
	v_mov_b32_e32 v91, v133
	v_mov_b32_e32 v92, v133
	v_mov_b32_e32 v93, v133
	v_mov_b32_e32 v94, v133
	v_mov_b32_e32 v95, v133
	v_mov_b32_e32 v104, v133
	v_mov_b32_e32 v105, v133
	v_mov_b32_e32 v106, v133
	v_mov_b32_e32 v107, v133
	v_mov_b32_e32 v108, v133
	v_mov_b32_e32 v109, v133
	v_mov_b32_e32 v110, v133
	v_mov_b32_e32 v111, v133
	v_mov_b32_e32 v120, v133
	v_mov_b32_e32 v121, v133
	v_mov_b32_e32 v122, v133
	v_mov_b32_e32 v123, v133
	v_mov_b32_e32 v124, v133
	v_mov_b32_e32 v125, v133
	v_mov_b32_e32 v126, v133
	v_mov_b32_e32 v127, v133
	s_barrier
	.p2align 6

.LBB0_1088:
	s_add_i32 s17, s1, -2
	s_add_u32 s26, s26, 0x40080
	s_addc_u32 s27, s27, 0
	s_add_u32 s19, s28, 0x100
	v_mov_b32_e32 v0, 0
	s_addc_u32 s21, s29, 0
	s_mov_b32 s23, 0
	v_mov_b32_e32 v1, v0
	v_mov_b32_e32 v2, v0
	v_mov_b32_e32 v3, v0
	v_mov_b32_e32 v4, v0
	v_mov_b32_e32 v5, v0
	v_mov_b32_e32 v6, v0
	v_mov_b32_e32 v7, v0
	v_mov_b32_e32 v8, v0
	v_mov_b32_e32 v9, v0
	v_mov_b32_e32 v10, v0
	v_mov_b32_e32 v11, v0
	v_mov_b32_e32 v12, v0
	v_mov_b32_e32 v13, v0
	v_mov_b32_e32 v14, v0
	v_mov_b32_e32 v15, v0
	v_mov_b32_e32 v24, v0
	v_mov_b32_e32 v25, v0
	v_mov_b32_e32 v26, v0
	v_mov_b32_e32 v27, v0
	v_mov_b32_e32 v28, v0
	v_mov_b32_e32 v29, v0
	v_mov_b32_e32 v30, v0
	v_mov_b32_e32 v31, v0
	v_mov_b32_e32 v40, v0
	v_mov_b32_e32 v41, v0
	v_mov_b32_e32 v42, v0
	v_mov_b32_e32 v43, v0
	v_mov_b32_e32 v44, v0
	v_mov_b32_e32 v45, v0
	v_mov_b32_e32 v46, v0
	v_mov_b32_e32 v47, v0
	v_mov_b32_e32 v16, v0
	v_mov_b32_e32 v17, v0
	v_mov_b32_e32 v18, v0
	v_mov_b32_e32 v19, v0
	v_mov_b32_e32 v20, v0
	v_mov_b32_e32 v21, v0
	v_mov_b32_e32 v22, v0
	v_mov_b32_e32 v23, v0
	v_mov_b32_e32 v32, v0
	v_mov_b32_e32 v33, v0
	v_mov_b32_e32 v34, v0
	v_mov_b32_e32 v35, v0
	v_mov_b32_e32 v36, v0
	v_mov_b32_e32 v37, v0
	v_mov_b32_e32 v38, v0
	v_mov_b32_e32 v39, v0
	v_mov_b32_e32 v48, v0
	v_mov_b32_e32 v49, v0
	v_mov_b32_e32 v50, v0
	v_mov_b32_e32 v51, v0
	v_mov_b32_e32 v52, v0
	v_mov_b32_e32 v53, v0
	v_mov_b32_e32 v54, v0
	v_mov_b32_e32 v55, v0
	v_mov_b32_e32 v56, v0
	v_mov_b32_e32 v57, v0
	v_mov_b32_e32 v58, v0
	v_mov_b32_e32 v59, v0
	v_mov_b32_e32 v60, v0
	v_mov_b32_e32 v61, v0
	v_mov_b32_e32 v62, v0
	v_mov_b32_e32 v63, v0
	v_mov_b32_e32 v64, v0
	v_mov_b32_e32 v65, v0
	v_mov_b32_e32 v66, v0
	v_mov_b32_e32 v67, v0
	v_mov_b32_e32 v68, v0
	v_mov_b32_e32 v69, v0
	v_mov_b32_e32 v70, v0
	v_mov_b32_e32 v71, v0
	v_mov_b32_e32 v72, v0
	v_mov_b32_e32 v73, v0
	v_mov_b32_e32 v74, v0
	v_mov_b32_e32 v75, v0
	v_mov_b32_e32 v76, v0
	v_mov_b32_e32 v77, v0
	v_mov_b32_e32 v78, v0
	v_mov_b32_e32 v79, v0
	v_mov_b32_e32 v88, v0
	v_mov_b32_e32 v89, v0
	v_mov_b32_e32 v90, v0
	v_mov_b32_e32 v91, v0
	v_mov_b32_e32 v92, v0
	v_mov_b32_e32 v93, v0
	v_mov_b32_e32 v94, v0
	v_mov_b32_e32 v95, v0
	v_mov_b32_e32 v104, v0
	v_mov_b32_e32 v105, v0
	v_mov_b32_e32 v106, v0
	v_mov_b32_e32 v107, v0
	v_mov_b32_e32 v108, v0
	v_mov_b32_e32 v109, v0
	v_mov_b32_e32 v110, v0
	v_mov_b32_e32 v111, v0
	v_mov_b32_e32 v80, v0
	v_mov_b32_e32 v81, v0
	v_mov_b32_e32 v82, v0
	v_mov_b32_e32 v83, v0
	v_mov_b32_e32 v84, v0
	v_mov_b32_e32 v85, v0
	v_mov_b32_e32 v86, v0
	v_mov_b32_e32 v87, v0
	v_mov_b32_e32 v96, v0
	v_mov_b32_e32 v97, v0
	v_mov_b32_e32 v98, v0
	v_mov_b32_e32 v99, v0
	v_mov_b32_e32 v100, v0
	v_mov_b32_e32 v101, v0
	v_mov_b32_e32 v102, v0
	v_mov_b32_e32 v103, v0
	v_mov_b32_e32 v112, v0
	v_mov_b32_e32 v113, v0
	v_mov_b32_e32 v114, v0
	v_mov_b32_e32 v115, v0
	v_mov_b32_e32 v116, v0
	v_mov_b32_e32 v117, v0
	v_mov_b32_e32 v118, v0
	v_mov_b32_e32 v119, v0
	v_mov_b32_e32 v120, v0
	v_mov_b32_e32 v121, v0
	v_mov_b32_e32 v122, v0
	v_mov_b32_e32 v123, v0
	v_mov_b32_e32 v124, v0
	v_mov_b32_e32 v125, v0
	v_mov_b32_e32 v126, v0
	v_mov_b32_e32 v127, v0
	.p2align 6

.LBB0_1243:
	s_ashr_i32 s83, s82, 31
	s_lshl_b64 s[30:31], s[82:83], 19
	v_readlane_b32 s36, v235, 56
	v_readlane_b32 s37, v235, 57
	s_add_u32 s36, s36, s30
	s_addc_u32 s37, s37, s31
	s_and_b64 s[30:31], s[16:17], exec
	s_cselect_b32 s9, s37, s41
	s_cselect_b32 s11, s36, s40
	s_ashr_i32 s91, s90, 31
	s_lshl_b64 s[30:31], s[90:91], 19
	v_readlane_b32 s38, v235, 26
	v_readlane_b32 s39, v235, 27
	s_add_u32 s38, s38, s30
	s_addc_u32 s39, s39, s31
	s_and_b64 s[30:31], s[16:17], exec
	s_cselect_b32 s30, s39, s43
	s_cselect_b32 s31, s38, s42
	s_add_u32 s83, s42, 0x100
	v_mov_b32_e32 v4, 0
	s_addc_u32 s91, s43, 0
	s_mov_b32 vcc_lo, -2
	v_mov_b32_e32 v5, v4
	v_mov_b32_e32 v6, v4
	v_mov_b32_e32 v7, v4
	v_mov_b32_e32 v0, v4
	v_mov_b32_e32 v1, v4
	v_mov_b32_e32 v2, v4
	v_mov_b32_e32 v3, v4
	v_mov_b32_e32 v28, v4
	v_mov_b32_e32 v29, v4
	v_mov_b32_e32 v30, v4
	v_mov_b32_e32 v31, v4
	v_mov_b32_e32 v20, v4
	v_mov_b32_e32 v21, v4
	v_mov_b32_e32 v22, v4
	v_mov_b32_e32 v23, v4
	v_mov_b32_e32 v24, v4
	v_mov_b32_e32 v25, v4
	v_mov_b32_e32 v26, v4
	v_mov_b32_e32 v27, v4
	v_mov_b32_e32 v32, v4
	v_mov_b32_e32 v33, v4
	v_mov_b32_e32 v34, v4
	v_mov_b32_e32 v35, v4
	v_mov_b32_e32 v44, v4
	v_mov_b32_e32 v45, v4
	v_mov_b32_e32 v46, v4
	v_mov_b32_e32 v47, v4
	v_mov_b32_e32 v40, v4
	v_mov_b32_e32 v41, v4
	v_mov_b32_e32 v42, v4
	v_mov_b32_e32 v43, v4
	v_mov_b32_e32 v12, v4
	v_mov_b32_e32 v13, v4
	v_mov_b32_e32 v14, v4
	v_mov_b32_e32 v15, v4
	v_mov_b32_e32 v8, v4
	v_mov_b32_e32 v9, v4
	v_mov_b32_e32 v10, v4
	v_mov_b32_e32 v11, v4
	v_mov_b32_e32 v128, v4
	v_mov_b32_e32 v129, v4
	v_mov_b32_e32 v130, v4
	v_mov_b32_e32 v131, v4
	v_mov_b32_e32 v132, v4
	v_mov_b32_e32 v133, v4
	v_mov_b32_e32 v134, v4
	v_mov_b32_e32 v135, v4
	v_mov_b32_e32 v48, v4
	v_mov_b32_e32 v49, v4
	v_mov_b32_e32 v50, v4
	v_mov_b32_e32 v51, v4
	v_mov_b32_e32 v52, v4
	v_mov_b32_e32 v53, v4
	v_mov_b32_e32 v54, v4
	v_mov_b32_e32 v55, v4
	v_mov_b32_e32 v36, v4
	v_mov_b32_e32 v37, v4
	v_mov_b32_e32 v38, v4
	v_mov_b32_e32 v39, v4
	v_mov_b32_e32 v16, v4
	v_mov_b32_e32 v17, v4
	v_mov_b32_e32 v18, v4
	v_mov_b32_e32 v19, v4
	v_mov_b32_e32 v56, v4
	v_mov_b32_e32 v57, v4
	v_mov_b32_e32 v58, v4
	v_mov_b32_e32 v59, v4
	v_mov_b32_e32 v60, v4
	v_mov_b32_e32 v61, v4
	v_mov_b32_e32 v62, v4
	v_mov_b32_e32 v63, v4
	v_mov_b32_e32 v64, v4
	v_mov_b32_e32 v65, v4
	v_mov_b32_e32 v66, v4
	v_mov_b32_e32 v67, v4
	v_mov_b32_e32 v68, v4
	v_mov_b32_e32 v69, v4
	v_mov_b32_e32 v70, v4
	v_mov_b32_e32 v71, v4
	v_mov_b32_e32 v72, v4
	v_mov_b32_e32 v73, v4
	v_mov_b32_e32 v74, v4
	v_mov_b32_e32 v75, v4
	v_mov_b32_e32 v76, v4
	v_mov_b32_e32 v77, v4
	v_mov_b32_e32 v78, v4
	v_mov_b32_e32 v79, v4
	v_mov_b32_e32 v80, v4
	v_mov_b32_e32 v81, v4
	v_mov_b32_e32 v82, v4
	v_mov_b32_e32 v83, v4
	v_mov_b32_e32 v88, v4
	v_mov_b32_e32 v89, v4
	v_mov_b32_e32 v90, v4
	v_mov_b32_e32 v91, v4
	v_mov_b32_e32 v136, v4
	v_mov_b32_e32 v137, v4
	v_mov_b32_e32 v138, v4
	v_mov_b32_e32 v139, v4
	v_mov_b32_e32 v140, v4
	v_mov_b32_e32 v141, v4
	v_mov_b32_e32 v142, v4
	v_mov_b32_e32 v143, v4
	v_mov_b32_e32 v84, v4
	v_mov_b32_e32 v85, v4
	v_mov_b32_e32 v86, v4
	v_mov_b32_e32 v87, v4
	v_mov_b32_e32 v92, v4
	v_mov_b32_e32 v93, v4
	v_mov_b32_e32 v94, v4
	v_mov_b32_e32 v95, v4
	v_mov_b32_e32 v116, v4
	v_mov_b32_e32 v117, v4
	v_mov_b32_e32 v118, v4
	v_mov_b32_e32 v119, v4
	v_mov_b32_e32 v112, v4
	v_mov_b32_e32 v113, v4
	v_mov_b32_e32 v114, v4
	v_mov_b32_e32 v115, v4
	v_mov_b32_e32 v100, v4
	v_mov_b32_e32 v101, v4
	v_mov_b32_e32 v102, v4
	v_mov_b32_e32 v103, v4
	v_mov_b32_e32 v96, v4
	v_mov_b32_e32 v97, v4
	v_mov_b32_e32 v98, v4
	v_mov_b32_e32 v99, v4
	.p2align 6

.LBB0_1364:
	s_add_i32 s11, s44, -2
	s_add_u32 s45, s22, 0x100
	v_mov_b32_e32 v0, 0
	s_addc_u32 s46, s23, 0
	s_mov_b32 s22, 0
	v_mov_b32_e32 v1, v0
	v_mov_b32_e32 v2, v0
	v_mov_b32_e32 v3, v0
	v_mov_b32_e32 v4, v0
	v_mov_b32_e32 v5, v0
	v_mov_b32_e32 v6, v0
	v_mov_b32_e32 v7, v0
	v_mov_b32_e32 v8, v0
	v_mov_b32_e32 v9, v0
	v_mov_b32_e32 v10, v0
	v_mov_b32_e32 v11, v0
	v_mov_b32_e32 v12, v0
	v_mov_b32_e32 v13, v0
	v_mov_b32_e32 v14, v0
	v_mov_b32_e32 v15, v0
	v_mov_b32_e32 v24, v0
	v_mov_b32_e32 v25, v0
	v_mov_b32_e32 v26, v0
	v_mov_b32_e32 v27, v0
	v_mov_b32_e32 v28, v0
	v_mov_b32_e32 v29, v0
	v_mov_b32_e32 v30, v0
	v_mov_b32_e32 v31, v0
	v_mov_b32_e32 v40, v0
	v_mov_b32_e32 v41, v0
	v_mov_b32_e32 v42, v0
	v_mov_b32_e32 v43, v0
	v_mov_b32_e32 v44, v0
	v_mov_b32_e32 v45, v0
	v_mov_b32_e32 v46, v0
	v_mov_b32_e32 v47, v0
	v_mov_b32_e32 v16, v0
	v_mov_b32_e32 v17, v0
	v_mov_b32_e32 v18, v0
	v_mov_b32_e32 v19, v0
	v_mov_b32_e32 v20, v0
	v_mov_b32_e32 v21, v0
	v_mov_b32_e32 v22, v0
	v_mov_b32_e32 v23, v0
	v_mov_b32_e32 v32, v0
	v_mov_b32_e32 v33, v0
	v_mov_b32_e32 v34, v0
	v_mov_b32_e32 v35, v0
	v_mov_b32_e32 v36, v0
	v_mov_b32_e32 v37, v0
	v_mov_b32_e32 v38, v0
	v_mov_b32_e32 v39, v0
	v_mov_b32_e32 v48, v0
	v_mov_b32_e32 v49, v0
	v_mov_b32_e32 v50, v0
	v_mov_b32_e32 v51, v0
	v_mov_b32_e32 v52, v0
	v_mov_b32_e32 v53, v0
	v_mov_b32_e32 v54, v0
	v_mov_b32_e32 v55, v0
	v_mov_b32_e32 v56, v0
	v_mov_b32_e32 v57, v0
	v_mov_b32_e32 v58, v0
	v_mov_b32_e32 v59, v0
	v_mov_b32_e32 v60, v0
	v_mov_b32_e32 v61, v0
	v_mov_b32_e32 v62, v0
	v_mov_b32_e32 v63, v0
	v_mov_b32_e32 v64, v0
	v_mov_b32_e32 v65, v0
	v_mov_b32_e32 v66, v0
	v_mov_b32_e32 v67, v0
	v_mov_b32_e32 v68, v0
	v_mov_b32_e32 v69, v0
	v_mov_b32_e32 v70, v0
	v_mov_b32_e32 v71, v0
	v_mov_b32_e32 v72, v0
	v_mov_b32_e32 v73, v0
	v_mov_b32_e32 v74, v0
	v_mov_b32_e32 v75, v0
	v_mov_b32_e32 v76, v0
	v_mov_b32_e32 v77, v0
	v_mov_b32_e32 v78, v0
	v_mov_b32_e32 v79, v0
	v_mov_b32_e32 v88, v0
	v_mov_b32_e32 v89, v0
	v_mov_b32_e32 v90, v0
	v_mov_b32_e32 v91, v0
	v_mov_b32_e32 v92, v0
	v_mov_b32_e32 v93, v0
	v_mov_b32_e32 v94, v0
	v_mov_b32_e32 v95, v0
	v_mov_b32_e32 v104, v0
	v_mov_b32_e32 v105, v0
	v_mov_b32_e32 v106, v0
	v_mov_b32_e32 v107, v0
	v_mov_b32_e32 v108, v0
	v_mov_b32_e32 v109, v0
	v_mov_b32_e32 v110, v0
	v_mov_b32_e32 v111, v0
	v_mov_b32_e32 v80, v0
	v_mov_b32_e32 v81, v0
	v_mov_b32_e32 v82, v0
	v_mov_b32_e32 v83, v0
	v_mov_b32_e32 v84, v0
	v_mov_b32_e32 v85, v0
	v_mov_b32_e32 v86, v0
	v_mov_b32_e32 v87, v0
	v_mov_b32_e32 v96, v0
	v_mov_b32_e32 v97, v0
	v_mov_b32_e32 v98, v0
	v_mov_b32_e32 v99, v0
	v_mov_b32_e32 v100, v0
	v_mov_b32_e32 v101, v0
	v_mov_b32_e32 v102, v0
	v_mov_b32_e32 v103, v0
	v_mov_b32_e32 v112, v0
	v_mov_b32_e32 v113, v0
	v_mov_b32_e32 v114, v0
	v_mov_b32_e32 v115, v0
	v_mov_b32_e32 v116, v0
	v_mov_b32_e32 v117, v0
	v_mov_b32_e32 v118, v0
	v_mov_b32_e32 v119, v0
	v_mov_b32_e32 v120, v0
	v_mov_b32_e32 v121, v0
	v_mov_b32_e32 v122, v0
	v_mov_b32_e32 v123, v0
	v_mov_b32_e32 v124, v0
	v_mov_b32_e32 v125, v0
	v_mov_b32_e32 v126, v0
	v_mov_b32_e32 v127, v0
	.p2align 6

.LBB0_1560:
	s_ashr_i32 s9, s8, 31
	s_lshl_b64 s[12:13], s[8:9], 19
	s_add_u32 s9, s86, s12
	s_addc_u32 s11, s87, s13
	s_and_b64 s[12:13], s[16:17], exec
	s_cselect_b32 s13, s11, s21
	s_cselect_b32 s12, s9, s20
	s_ashr_i32 s11, s10, 31
	s_lshl_b64 s[14:15], s[10:11], 19
	v_readlane_b32 s24, v235, 22
	v_readlane_b32 s25, v235, 23
	s_add_u32 s9, s24, s14
	s_addc_u32 s11, s25, s15
	s_and_b64 s[14:15], s[16:17], exec
	s_cselect_b32 s15, s11, s23
	s_cselect_b32 s14, s9, s22
	s_cmp_lt_i32 s41, 1
	s_cbranch_scc1 .LBB0_1568
	s_add_i32 s9, s41, -2
	s_add_u32 s20, s20, 0x40080
	s_addc_u32 s21, s21, 0
	s_add_u32 s11, s22, 0x100
	v_mov_b32_e32 v0, 0
	s_addc_u32 s42, s23, 0
	s_mov_b32 s22, 0
	v_mov_b32_e32 v1, v0
	v_mov_b32_e32 v2, v0
	v_mov_b32_e32 v3, v0
	v_mov_b32_e32 v4, v0
	v_mov_b32_e32 v5, v0
	v_mov_b32_e32 v6, v0
	v_mov_b32_e32 v7, v0
	v_mov_b32_e32 v16, v0
	v_mov_b32_e32 v17, v0
	v_mov_b32_e32 v18, v0
	v_mov_b32_e32 v19, v0
	v_mov_b32_e32 v20, v0
	v_mov_b32_e32 v21, v0
	v_mov_b32_e32 v22, v0
	v_mov_b32_e32 v23, v0
	v_mov_b32_e32 v32, v0
	v_mov_b32_e32 v33, v0
	v_mov_b32_e32 v34, v0
	v_mov_b32_e32 v35, v0
	v_mov_b32_e32 v36, v0
	v_mov_b32_e32 v37, v0
	v_mov_b32_e32 v38, v0
	v_mov_b32_e32 v39, v0
	v_mov_b32_e32 v48, v0
	v_mov_b32_e32 v49, v0
	v_mov_b32_e32 v50, v0
	v_mov_b32_e32 v51, v0
	v_mov_b32_e32 v52, v0
	v_mov_b32_e32 v53, v0
	v_mov_b32_e32 v54, v0
	v_mov_b32_e32 v55, v0
	v_mov_b32_e32 v8, v0
	v_mov_b32_e32 v9, v0
	v_mov_b32_e32 v10, v0
	v_mov_b32_e32 v11, v0
	v_mov_b32_e32 v12, v0
	v_mov_b32_e32 v13, v0
	v_mov_b32_e32 v14, v0
	v_mov_b32_e32 v15, v0
	v_mov_b32_e32 v24, v0
	v_mov_b32_e32 v25, v0
	v_mov_b32_e32 v26, v0
	v_mov_b32_e32 v27, v0
	v_mov_b32_e32 v28, v0
	v_mov_b32_e32 v29, v0
	v_mov_b32_e32 v30, v0
	v_mov_b32_e32 v31, v0
	v_mov_b32_e32 v40, v0
	v_mov_b32_e32 v41, v0
	v_mov_b32_e32 v42, v0
	v_mov_b32_e32 v43, v0
	v_mov_b32_e32 v44, v0
	v_mov_b32_e32 v45, v0
	v_mov_b32_e32 v46, v0
	v_mov_b32_e32 v47, v0
	v_mov_b32_e32 v56, v0
	v_mov_b32_e32 v57, v0
	v_mov_b32_e32 v58, v0
	v_mov_b32_e32 v59, v0
	v_mov_b32_e32 v60, v0
	v_mov_b32_e32 v61, v0
	v_mov_b32_e32 v62, v0
	v_mov_b32_e32 v63, v0
	v_mov_b32_e32 v64, v0
	v_mov_b32_e32 v65, v0
	v_mov_b32_e32 v66, v0
	v_mov_b32_e32 v67, v0
	v_mov_b32_e32 v68, v0
	v_mov_b32_e32 v69, v0
	v_mov_b32_e32 v70, v0
	v_mov_b32_e32 v71, v0
	v_mov_b32_e32 v80, v0
	v_mov_b32_e32 v81, v0
	v_mov_b32_e32 v82, v0
	v_mov_b32_e32 v83, v0
	v_mov_b32_e32 v84, v0
	v_mov_b32_e32 v85, v0
	v_mov_b32_e32 v86, v0
	v_mov_b32_e32 v87, v0
	v_mov_b32_e32 v96, v0
	v_mov_b32_e32 v97, v0
	v_mov_b32_e32 v98, v0
	v_mov_b32_e32 v99, v0
	v_mov_b32_e32 v100, v0
	v_mov_b32_e32 v101, v0
	v_mov_b32_e32 v102, v0
	v_mov_b32_e32 v103, v0
	v_mov_b32_e32 v112, v0
	v_mov_b32_e32 v113, v0
	v_mov_b32_e32 v114, v0
	v_mov_b32_e32 v115, v0
	v_mov_b32_e32 v116, v0
	v_mov_b32_e32 v117, v0
	v_mov_b32_e32 v118, v0
	v_mov_b32_e32 v119, v0
	v_mov_b32_e32 v72, v0
	v_mov_b32_e32 v73, v0
	v_mov_b32_e32 v74, v0
	v_mov_b32_e32 v75, v0
	v_mov_b32_e32 v76, v0
	v_mov_b32_e32 v77, v0
	v_mov_b32_e32 v78, v0
	v_mov_b32_e32 v79, v0
	v_mov_b32_e32 v88, v0
	v_mov_b32_e32 v89, v0
	v_mov_b32_e32 v90, v0
	v_mov_b32_e32 v91, v0
	v_mov_b32_e32 v92, v0
	v_mov_b32_e32 v93, v0
	v_mov_b32_e32 v94, v0
	v_mov_b32_e32 v95, v0
	v_mov_b32_e32 v104, v0
	v_mov_b32_e32 v105, v0
	v_mov_b32_e32 v106, v0
	v_mov_b32_e32 v107, v0
	v_mov_b32_e32 v108, v0
	v_mov_b32_e32 v109, v0
	v_mov_b32_e32 v110, v0
	v_mov_b32_e32 v111, v0
	v_mov_b32_e32 v120, v0
	v_mov_b32_e32 v121, v0
	v_mov_b32_e32 v122, v0
	v_mov_b32_e32 v123, v0
	v_mov_b32_e32 v124, v0
	v_mov_b32_e32 v125, v0
	v_mov_b32_e32 v126, v0
	v_mov_b32_e32 v127, v0
	.p2align 6

.LBB0_1797:
	s_add_i32 s13, s1, -2
	s_add_u32 s26, s26, 0x40080
	s_addc_u32 s27, s27, 0
	s_add_u32 s15, s28, 0x100
	v_mov_b32_e32 v0, 0
	s_addc_u32 s21, s29, 0
	s_mov_b32 s23, 0
	v_mov_b32_e32 v1, v0
	v_mov_b32_e32 v2, v0
	v_mov_b32_e32 v3, v0
	v_mov_b32_e32 v4, v0
	v_mov_b32_e32 v5, v0
	v_mov_b32_e32 v6, v0
	v_mov_b32_e32 v7, v0
	v_mov_b32_e32 v8, v0
	v_mov_b32_e32 v9, v0
	v_mov_b32_e32 v10, v0
	v_mov_b32_e32 v11, v0
	v_mov_b32_e32 v12, v0
	v_mov_b32_e32 v13, v0
	v_mov_b32_e32 v14, v0
	v_mov_b32_e32 v15, v0
	v_mov_b32_e32 v24, v0
	v_mov_b32_e32 v25, v0
	v_mov_b32_e32 v26, v0
	v_mov_b32_e32 v27, v0
	v_mov_b32_e32 v28, v0
	v_mov_b32_e32 v29, v0
	v_mov_b32_e32 v30, v0
	v_mov_b32_e32 v31, v0
	v_mov_b32_e32 v40, v0
	v_mov_b32_e32 v41, v0
	v_mov_b32_e32 v42, v0
	v_mov_b32_e32 v43, v0
	v_mov_b32_e32 v44, v0
	v_mov_b32_e32 v45, v0
	v_mov_b32_e32 v46, v0
	v_mov_b32_e32 v47, v0
	v_mov_b32_e32 v16, v0
	v_mov_b32_e32 v17, v0
	v_mov_b32_e32 v18, v0
	v_mov_b32_e32 v19, v0
	v_mov_b32_e32 v20, v0
	v_mov_b32_e32 v21, v0
	v_mov_b32_e32 v22, v0
	v_mov_b32_e32 v23, v0
	v_mov_b32_e32 v32, v0
	v_mov_b32_e32 v33, v0
	v_mov_b32_e32 v34, v0
	v_mov_b32_e32 v35, v0
	v_mov_b32_e32 v36, v0
	v_mov_b32_e32 v37, v0
	v_mov_b32_e32 v38, v0
	v_mov_b32_e32 v39, v0
	v_mov_b32_e32 v48, v0
	v_mov_b32_e32 v49, v0
	v_mov_b32_e32 v50, v0
	v_mov_b32_e32 v51, v0
	v_mov_b32_e32 v52, v0
	v_mov_b32_e32 v53, v0
	v_mov_b32_e32 v54, v0
	v_mov_b32_e32 v55, v0
	v_mov_b32_e32 v56, v0
	v_mov_b32_e32 v57, v0
	v_mov_b32_e32 v58, v0
	v_mov_b32_e32 v59, v0
	v_mov_b32_e32 v60, v0
	v_mov_b32_e32 v61, v0
	v_mov_b32_e32 v62, v0
	v_mov_b32_e32 v63, v0
	v_mov_b32_e32 v64, v0
	v_mov_b32_e32 v65, v0
	v_mov_b32_e32 v66, v0
	v_mov_b32_e32 v67, v0
	v_mov_b32_e32 v68, v0
	v_mov_b32_e32 v69, v0
	v_mov_b32_e32 v70, v0
	v_mov_b32_e32 v71, v0
	v_mov_b32_e32 v72, v0
	v_mov_b32_e32 v73, v0
	v_mov_b32_e32 v74, v0
	v_mov_b32_e32 v75, v0
	v_mov_b32_e32 v76, v0
	v_mov_b32_e32 v77, v0
	v_mov_b32_e32 v78, v0
	v_mov_b32_e32 v79, v0
	v_mov_b32_e32 v88, v0
	v_mov_b32_e32 v89, v0
	v_mov_b32_e32 v90, v0
	v_mov_b32_e32 v91, v0
	v_mov_b32_e32 v92, v0
	v_mov_b32_e32 v93, v0
	v_mov_b32_e32 v94, v0
	v_mov_b32_e32 v95, v0
	v_mov_b32_e32 v104, v0
	v_mov_b32_e32 v105, v0
	v_mov_b32_e32 v106, v0
	v_mov_b32_e32 v107, v0
	v_mov_b32_e32 v108, v0
	v_mov_b32_e32 v109, v0
	v_mov_b32_e32 v110, v0
	v_mov_b32_e32 v111, v0
	v_mov_b32_e32 v80, v0
	v_mov_b32_e32 v81, v0
	v_mov_b32_e32 v82, v0
	v_mov_b32_e32 v83, v0
	v_mov_b32_e32 v84, v0
	v_mov_b32_e32 v85, v0
	v_mov_b32_e32 v86, v0
	v_mov_b32_e32 v87, v0
	v_mov_b32_e32 v96, v0
	v_mov_b32_e32 v97, v0
	v_mov_b32_e32 v98, v0
	v_mov_b32_e32 v99, v0
	v_mov_b32_e32 v100, v0
	v_mov_b32_e32 v101, v0
	v_mov_b32_e32 v102, v0
	v_mov_b32_e32 v103, v0
	v_mov_b32_e32 v112, v0
	v_mov_b32_e32 v113, v0
	v_mov_b32_e32 v114, v0
	v_mov_b32_e32 v115, v0
	v_mov_b32_e32 v116, v0
	v_mov_b32_e32 v117, v0
	v_mov_b32_e32 v118, v0
	v_mov_b32_e32 v119, v0
	v_mov_b32_e32 v120, v0
	v_mov_b32_e32 v121, v0
	v_mov_b32_e32 v122, v0
	v_mov_b32_e32 v123, v0
	v_mov_b32_e32 v124, v0
	v_mov_b32_e32 v125, v0
	v_mov_b32_e32 v126, v0
	v_mov_b32_e32 v127, v0
	.p2align 6

.LBB0_1952:
	s_ashr_i32 s83, s82, 31
	s_lshl_b64 s[30:31], s[82:83], 19
	v_readlane_b32 s36, v235, 56
	v_readlane_b32 s37, v235, 57
	s_add_u32 s36, s36, s30
	s_addc_u32 s37, s37, s31
	s_and_b64 s[30:31], s[18:19], exec
	s_cselect_b32 s9, s37, s41
	s_cselect_b32 s11, s36, s40
	s_ashr_i32 s91, s90, 31
	s_lshl_b64 s[30:31], s[90:91], 19
	v_readlane_b32 s38, v235, 26
	v_readlane_b32 s39, v235, 27
	s_add_u32 s38, s38, s30
	s_addc_u32 s39, s39, s31
	s_and_b64 s[30:31], s[18:19], exec
	s_cselect_b32 s30, s39, s43
	s_cselect_b32 s31, s38, s42
	s_add_u32 s83, s42, 0x100
	v_mov_b32_e32 v4, 0
	s_addc_u32 s91, s43, 0
	s_mov_b32 vcc_lo, -2
	v_mov_b32_e32 v5, v4
	v_mov_b32_e32 v6, v4
	v_mov_b32_e32 v7, v4
	v_mov_b32_e32 v0, v4
	v_mov_b32_e32 v1, v4
	v_mov_b32_e32 v2, v4
	v_mov_b32_e32 v3, v4
	v_mov_b32_e32 v28, v4
	v_mov_b32_e32 v29, v4
	v_mov_b32_e32 v30, v4
	v_mov_b32_e32 v31, v4
	v_mov_b32_e32 v20, v4
	v_mov_b32_e32 v21, v4
	v_mov_b32_e32 v22, v4
	v_mov_b32_e32 v23, v4
	v_mov_b32_e32 v24, v4
	v_mov_b32_e32 v25, v4
	v_mov_b32_e32 v26, v4
	v_mov_b32_e32 v27, v4
	v_mov_b32_e32 v32, v4
	v_mov_b32_e32 v33, v4
	v_mov_b32_e32 v34, v4
	v_mov_b32_e32 v35, v4
	v_mov_b32_e32 v44, v4
	v_mov_b32_e32 v45, v4
	v_mov_b32_e32 v46, v4
	v_mov_b32_e32 v47, v4
	v_mov_b32_e32 v40, v4
	v_mov_b32_e32 v41, v4
	v_mov_b32_e32 v42, v4
	v_mov_b32_e32 v43, v4
	v_mov_b32_e32 v12, v4
	v_mov_b32_e32 v13, v4
	v_mov_b32_e32 v14, v4
	v_mov_b32_e32 v15, v4
	v_mov_b32_e32 v8, v4
	v_mov_b32_e32 v9, v4
	v_mov_b32_e32 v10, v4
	v_mov_b32_e32 v11, v4
	v_mov_b32_e32 v128, v4
	v_mov_b32_e32 v129, v4
	v_mov_b32_e32 v130, v4
	v_mov_b32_e32 v131, v4
	v_mov_b32_e32 v132, v4
	v_mov_b32_e32 v133, v4
	v_mov_b32_e32 v134, v4
	v_mov_b32_e32 v135, v4
	v_mov_b32_e32 v48, v4
	v_mov_b32_e32 v49, v4
	v_mov_b32_e32 v50, v4
	v_mov_b32_e32 v51, v4
	v_mov_b32_e32 v52, v4
	v_mov_b32_e32 v53, v4
	v_mov_b32_e32 v54, v4
	v_mov_b32_e32 v55, v4
	v_mov_b32_e32 v36, v4
	v_mov_b32_e32 v37, v4
	v_mov_b32_e32 v38, v4
	v_mov_b32_e32 v39, v4
	v_mov_b32_e32 v16, v4
	v_mov_b32_e32 v17, v4
	v_mov_b32_e32 v18, v4
	v_mov_b32_e32 v19, v4
	v_mov_b32_e32 v56, v4
	v_mov_b32_e32 v57, v4
	v_mov_b32_e32 v58, v4
	v_mov_b32_e32 v59, v4
	v_mov_b32_e32 v60, v4
	v_mov_b32_e32 v61, v4
	v_mov_b32_e32 v62, v4
	v_mov_b32_e32 v63, v4
	v_mov_b32_e32 v64, v4
	v_mov_b32_e32 v65, v4
	v_mov_b32_e32 v66, v4
	v_mov_b32_e32 v67, v4
	v_mov_b32_e32 v68, v4
	v_mov_b32_e32 v69, v4
	v_mov_b32_e32 v70, v4
	v_mov_b32_e32 v71, v4
	v_mov_b32_e32 v72, v4
	v_mov_b32_e32 v73, v4
	v_mov_b32_e32 v74, v4
	v_mov_b32_e32 v75, v4
	v_mov_b32_e32 v76, v4
	v_mov_b32_e32 v77, v4
	v_mov_b32_e32 v78, v4
	v_mov_b32_e32 v79, v4
	v_mov_b32_e32 v80, v4
	v_mov_b32_e32 v81, v4
	v_mov_b32_e32 v82, v4
	v_mov_b32_e32 v83, v4
	v_mov_b32_e32 v88, v4
	v_mov_b32_e32 v89, v4
	v_mov_b32_e32 v90, v4
	v_mov_b32_e32 v91, v4
	v_mov_b32_e32 v136, v4
	v_mov_b32_e32 v137, v4
	v_mov_b32_e32 v138, v4
	v_mov_b32_e32 v139, v4
	v_mov_b32_e32 v140, v4
	v_mov_b32_e32 v141, v4
	v_mov_b32_e32 v142, v4
	v_mov_b32_e32 v143, v4
	v_mov_b32_e32 v84, v4
	v_mov_b32_e32 v85, v4
	v_mov_b32_e32 v86, v4
	v_mov_b32_e32 v87, v4
	v_mov_b32_e32 v92, v4
	v_mov_b32_e32 v93, v4
	v_mov_b32_e32 v94, v4
	v_mov_b32_e32 v95, v4
	v_mov_b32_e32 v116, v4
	v_mov_b32_e32 v117, v4
	v_mov_b32_e32 v118, v4
	v_mov_b32_e32 v119, v4
	v_mov_b32_e32 v112, v4
	v_mov_b32_e32 v113, v4
	v_mov_b32_e32 v114, v4
	v_mov_b32_e32 v115, v4
	v_mov_b32_e32 v100, v4
	v_mov_b32_e32 v101, v4
	v_mov_b32_e32 v102, v4
	v_mov_b32_e32 v103, v4
	v_mov_b32_e32 v96, v4
	v_mov_b32_e32 v97, v4
	v_mov_b32_e32 v98, v4
	v_mov_b32_e32 v99, v4
	.p2align 6

.LBB0_2269:
	s_ashr_i32 s11, s10, 31
	s_lshl_b64 s[14:15], s[10:11], 19
	s_add_u32 s11, s86, s14
	s_addc_u32 s13, s87, s15
	s_and_b64 s[14:15], s[4:5], exec
	s_cselect_b32 s15, s13, s21
	s_cselect_b32 s14, s11, s20
	s_ashr_i32 s13, s12, 31
	s_lshl_b64 s[16:17], s[12:13], 19
	v_readlane_b32 s24, v235, 22
	v_readlane_b32 s25, v235, 23
	s_add_u32 s11, s24, s16
	s_addc_u32 s13, s25, s17
	s_and_b64 s[16:17], s[4:5], exec
	s_cselect_b32 s17, s13, s23
	s_cselect_b32 s16, s11, s22
	s_cmp_lt_i32 s41, 1
	s_cbranch_scc1 .LBB0_2277
	s_add_i32 s11, s41, -2
	s_add_u32 s20, s20, 0x40080
	s_addc_u32 s21, s21, 0
	s_add_u32 s13, s22, 0x100
	v_mov_b32_e32 v0, 0
	s_addc_u32 s42, s23, 0
	s_mov_b32 s22, 0
	v_mov_b32_e32 v1, v0
	v_mov_b32_e32 v2, v0
	v_mov_b32_e32 v3, v0
	v_mov_b32_e32 v4, v0
	v_mov_b32_e32 v5, v0
	v_mov_b32_e32 v6, v0
	v_mov_b32_e32 v7, v0
	v_mov_b32_e32 v16, v0
	v_mov_b32_e32 v17, v0
	v_mov_b32_e32 v18, v0
	v_mov_b32_e32 v19, v0
	v_mov_b32_e32 v20, v0
	v_mov_b32_e32 v21, v0
	v_mov_b32_e32 v22, v0
	v_mov_b32_e32 v23, v0
	v_mov_b32_e32 v32, v0
	v_mov_b32_e32 v33, v0
	v_mov_b32_e32 v34, v0
	v_mov_b32_e32 v35, v0
	v_mov_b32_e32 v36, v0
	v_mov_b32_e32 v37, v0
	v_mov_b32_e32 v38, v0
	v_mov_b32_e32 v39, v0
	v_mov_b32_e32 v48, v0
	v_mov_b32_e32 v49, v0
	v_mov_b32_e32 v50, v0
	v_mov_b32_e32 v51, v0
	v_mov_b32_e32 v52, v0
	v_mov_b32_e32 v53, v0
	v_mov_b32_e32 v54, v0
	v_mov_b32_e32 v55, v0
	v_mov_b32_e32 v8, v0
	v_mov_b32_e32 v9, v0
	v_mov_b32_e32 v10, v0
	v_mov_b32_e32 v11, v0
	v_mov_b32_e32 v12, v0
	v_mov_b32_e32 v13, v0
	v_mov_b32_e32 v14, v0
	v_mov_b32_e32 v15, v0
	v_mov_b32_e32 v24, v0
	v_mov_b32_e32 v25, v0
	v_mov_b32_e32 v26, v0
	v_mov_b32_e32 v27, v0
	v_mov_b32_e32 v28, v0
	v_mov_b32_e32 v29, v0
	v_mov_b32_e32 v30, v0
	v_mov_b32_e32 v31, v0
	v_mov_b32_e32 v40, v0
	v_mov_b32_e32 v41, v0
	v_mov_b32_e32 v42, v0
	v_mov_b32_e32 v43, v0
	v_mov_b32_e32 v44, v0
	v_mov_b32_e32 v45, v0
	v_mov_b32_e32 v46, v0
	v_mov_b32_e32 v47, v0
	v_mov_b32_e32 v56, v0
	v_mov_b32_e32 v57, v0
	v_mov_b32_e32 v58, v0
	v_mov_b32_e32 v59, v0
	v_mov_b32_e32 v60, v0
	v_mov_b32_e32 v61, v0
	v_mov_b32_e32 v62, v0
	v_mov_b32_e32 v63, v0
	v_mov_b32_e32 v64, v0
	v_mov_b32_e32 v65, v0
	v_mov_b32_e32 v66, v0
	v_mov_b32_e32 v67, v0
	v_mov_b32_e32 v68, v0
	v_mov_b32_e32 v69, v0
	v_mov_b32_e32 v70, v0
	v_mov_b32_e32 v71, v0
	v_mov_b32_e32 v80, v0
	v_mov_b32_e32 v81, v0
	v_mov_b32_e32 v82, v0
	v_mov_b32_e32 v83, v0
	v_mov_b32_e32 v84, v0
	v_mov_b32_e32 v85, v0
	v_mov_b32_e32 v86, v0
	v_mov_b32_e32 v87, v0
	v_mov_b32_e32 v96, v0
	v_mov_b32_e32 v97, v0
	v_mov_b32_e32 v98, v0
	v_mov_b32_e32 v99, v0
	v_mov_b32_e32 v100, v0
	v_mov_b32_e32 v101, v0
	v_mov_b32_e32 v102, v0
	v_mov_b32_e32 v103, v0
	v_mov_b32_e32 v112, v0
	v_mov_b32_e32 v113, v0
	v_mov_b32_e32 v114, v0
	v_mov_b32_e32 v115, v0
	v_mov_b32_e32 v116, v0
	v_mov_b32_e32 v117, v0
	v_mov_b32_e32 v118, v0
	v_mov_b32_e32 v119, v0
	v_mov_b32_e32 v72, v0
	v_mov_b32_e32 v73, v0
	v_mov_b32_e32 v74, v0
	v_mov_b32_e32 v75, v0
	v_mov_b32_e32 v76, v0
	v_mov_b32_e32 v77, v0
	v_mov_b32_e32 v78, v0
	v_mov_b32_e32 v79, v0
	v_mov_b32_e32 v88, v0
	v_mov_b32_e32 v89, v0
	v_mov_b32_e32 v90, v0
	v_mov_b32_e32 v91, v0
	v_mov_b32_e32 v92, v0
	v_mov_b32_e32 v93, v0
	v_mov_b32_e32 v94, v0
	v_mov_b32_e32 v95, v0
	v_mov_b32_e32 v104, v0
	v_mov_b32_e32 v105, v0
	v_mov_b32_e32 v106, v0
	v_mov_b32_e32 v107, v0
	v_mov_b32_e32 v108, v0
	v_mov_b32_e32 v109, v0
	v_mov_b32_e32 v110, v0
	v_mov_b32_e32 v111, v0
	v_mov_b32_e32 v120, v0
	v_mov_b32_e32 v121, v0
	v_mov_b32_e32 v122, v0
	v_mov_b32_e32 v123, v0
	v_mov_b32_e32 v124, v0
	v_mov_b32_e32 v125, v0
	v_mov_b32_e32 v126, v0
	v_mov_b32_e32 v127, v0
	.p2align 6

.LBB0_2336:
	v_and_b32_e32 v14, 15, v140
	v_readlane_b32 s10, v235, 34
	v_and_b32_e32 v17, 48, v140
	v_ashrrev_i32_e32 v15, 6, v140
	v_or_b32_e32 v141, s10, v14
	v_lshlrev_b32_e32 v16, 6, v141
	s_movk_i32 s10, 0x3c0
	v_and_or_b32 v16, v16, s10, v17
	v_readlane_b32 s10, v235, 36
	s_add_i32 m0, s1, 0x18000
	s_waitcnt vmcnt(2)
	s_barrier
	v_lshl_add_u32 v18, v15, 10, s10
	v_readlane_b32 s10, v235, 38
	s_add_i32 s20, s1, 0x8000
	s_add_i32 s21, s1, 0xa000
	v_add_lshl_u32 v15, v15, s10, 10
	s_mov_b64 s[10:11], 0x80
	v_lshl_add_u64 v[6:7], v[6:7], 0, s[10:11]
	global_load_lds_dwordx4 v[6:7], off
	v_lshl_add_u64 v[4:5], v[4:5], 0, s[10:11]
	s_add_i32 m0, s1, 0x1a000
	v_lshl_add_u64 v[0:1], v[0:1], 0, s[10:11]
	global_load_lds_dwordx4 v[4:5], off
	s_mov_b32 m0, s20
	s_add_u32 s14, s6, 0x40080
	global_load_lds_dwordx4 v[0:1], off
	v_lshl_add_u64 v[0:1], v[2:3], 0, s[10:11]
	s_mov_b32 m0, s21
	s_addc_u32 s15, s7, 0
	global_load_lds_dwordx4 v[0:1], off
	s_add_i32 m0, s1, 0x1c000
	v_lshl_add_u64 v[0:1], s[14:15], 0, v[132:133]
	global_load_lds_dwordx4 v[0:1], off
	v_lshl_add_u64 v[0:1], s[14:15], 0, v[128:129]
	s_add_i32 m0, s1, 0x1e000
	s_ashr_i32 s13, s12, 31
	global_load_lds_dwordx4 v[0:1], off
	v_lshlrev_b32_e32 v0, 14, v11
	v_and_b32_e32 v0, 0xffff8000, v0
	s_lshl_b64 s[12:13], s[12:13], 19
	v_lshl_add_u32 v0, v12, 11, v0
	v_and_b32_e32 v1, 1, v11
	v_lshl_or_b32 v0, v1, 6, v0
	s_add_u32 s12, s78, s12
	v_lshl_add_u32 v0, v13, 1, v0
	v_mov_b32_e32 v1, v133
	s_addc_u32 s13, s79, s13
	v_lshl_add_u64 v[136:137], s[12:13], 0, v[0:1]
	v_lshlrev_b32_e32 v0, 14, v8
	v_lshl_or_b32 v14, v14, 6, v17
	v_lshlrev_b32_e32 v17, 2, v140
	v_and_b32_e32 v0, 0xffff8000, v0
	v_lshlrev_b32_e32 v19, 2, v141
	v_and_b32_e32 v17, 32, v17
	v_lshl_add_u32 v0, v9, 11, v0
	v_and_b32_e32 v1, 1, v8
	v_and_b32_e32 v19, 32, v19
	v_bitop3_b32 v14, v14, v15, v17 bitop3:0xde
	s_waitcnt vmcnt(6)
	v_lshl_or_b32 v0, v1, 6, v0
	s_add_i32 s25, 0, 0x10000
	s_add_i32 s27, 0, 0x14000
	s_add_i32 s29, 0, 0x18000
	s_add_i32 s31, 0, 0x1c000
	v_bitop3_b32 v16, v16, v18, v19 bitop3:0xde
	v_lshl_add_u32 v0, v10, 1, v0
	v_mov_b32_e32 v1, v133
	v_add_u32_e32 v142, s25, v14
	v_add_u32_e32 v143, s27, v14
	s_add_i32 s25, s25, s3
	s_add_i32 s27, s27, s3
	v_add_u32_e32 v145, s29, v14
	v_add_u32_e32 v146, s31, v14
	s_add_i32 s29, s29, s3
	s_add_i32 s31, s31, s3
	v_lshl_add_u64 v[138:139], s[12:13], 0, v[0:1]
	s_mov_b32 s22, -2
	s_mov_b64 s[12:13], 0x3840080
	v_add_u32_e32 v144, 0, v16
	s_add_i32 s23, s1, 0xc000
	s_add_i32 s24, s1, 0xe000
	s_add_i32 s26, s25, 0x2000
	s_add_i32 s28, s27, 0x2000
	s_add_i32 s30, s29, 0x2000
	s_add_i32 s36, s31, 0x2000
	v_mov_b32_e32 v0, v133
	v_mov_b32_e32 v2, v133
	v_mov_b32_e32 v3, v133
	v_mov_b32_e32 v4, v133
	v_mov_b32_e32 v5, v133
	v_mov_b32_e32 v6, v133
	v_mov_b32_e32 v7, v133
	v_mov_b32_e32 v16, v133
	v_mov_b32_e32 v17, v133
	v_mov_b32_e32 v18, v133
	v_mov_b32_e32 v19, v133
	v_mov_b32_e32 v20, v133
	v_mov_b32_e32 v21, v133
	v_mov_b32_e32 v22, v133
	v_mov_b32_e32 v23, v133
	v_mov_b32_e32 v32, v133
	v_mov_b32_e32 v33, v133
	v_mov_b32_e32 v34, v133
	v_mov_b32_e32 v35, v133
	v_mov_b32_e32 v36, v133
	v_mov_b32_e32 v37, v133
	v_mov_b32_e32 v38, v133
	v_mov_b32_e32 v39, v133
	v_mov_b32_e32 v48, v133
	v_mov_b32_e32 v49, v133
	v_mov_b32_e32 v50, v133
	v_mov_b32_e32 v51, v133
	v_mov_b32_e32 v52, v133
	v_mov_b32_e32 v53, v133
	v_mov_b32_e32 v54, v133
	v_mov_b32_e32 v55, v133
	v_mov_b32_e32 v8, v133
	v_mov_b32_e32 v9, v133
	v_mov_b32_e32 v10, v133
	v_mov_b32_e32 v11, v133
	v_mov_b32_e32 v12, v133
	v_mov_b32_e32 v13, v133
	v_mov_b32_e32 v14, v133
	v_mov_b32_e32 v15, v133
	v_mov_b32_e32 v24, v133
	v_mov_b32_e32 v25, v133
	v_mov_b32_e32 v26, v133
	v_mov_b32_e32 v27, v133
	v_mov_b32_e32 v28, v133
	v_mov_b32_e32 v29, v133
	v_mov_b32_e32 v30, v133
	v_mov_b32_e32 v31, v133
	v_mov_b32_e32 v40, v133
	v_mov_b32_e32 v41, v133
	v_mov_b32_e32 v42, v133
	v_mov_b32_e32 v43, v133
	v_mov_b32_e32 v44, v133
	v_mov_b32_e32 v45, v133
	v_mov_b32_e32 v46, v133
	v_mov_b32_e32 v47, v133
	v_mov_b32_e32 v56, v133
	v_mov_b32_e32 v57, v133
	v_mov_b32_e32 v58, v133
	v_mov_b32_e32 v59, v133
	v_mov_b32_e32 v60, v133
	v_mov_b32_e32 v61, v133
	v_mov_b32_e32 v62, v133
	v_mov_b32_e32 v63, v133
	v_mov_b32_e32 v64, v133
	v_mov_b32_e32 v65, v133
	v_mov_b32_e32 v66, v133
	v_mov_b32_e32 v67, v133
	v_mov_b32_e32 v68, v133
	v_mov_b32_e32 v69, v133
	v_mov_b32_e32 v70, v133
	v_mov_b32_e32 v71, v133
	v_mov_b32_e32 v72, v133
	v_mov_b32_e32 v73, v133
	v_mov_b32_e32 v74, v133
	v_mov_b32_e32 v75, v133
	v_mov_b32_e32 v80, v133
	v_mov_b32_e32 v81, v133
	v_mov_b32_e32 v82, v133
	v_mov_b32_e32 v83, v133
	v_mov_b32_e32 v96, v133
	v_mov_b32_e32 v97, v133
	v_mov_b32_e32 v98, v133
	v_mov_b32_e32 v99, v133
	v_mov_b32_e32 v100, v133
	v_mov_b32_e32 v101, v133
	v_mov_b32_e32 v102, v133
	v_mov_b32_e32 v103, v133
	v_mov_b32_e32 v112, v133
	v_mov_b32_e32 v113, v133
	v_mov_b32_e32 v114, v133
	v_mov_b32_e32 v115, v133
	v_mov_b32_e32 v116, v133
	v_mov_b32_e32 v117, v133
	v_mov_b32_e32 v118, v133
	v_mov_b32_e32 v119, v133
	v_mov_b32_e32 v76, v133
	v_mov_b32_e32 v77, v133
	v_mov_b32_e32 v78, v133
	v_mov_b32_e32 v79, v133
	v_mov_b32_e32 v84, v133
	v_mov_b32_e32 v85, v133
	v_mov_b32_e32 v86, v133
	v_mov_b32_e32 v87, v133
	v_mov_b32_e32 v88, v133
	v_mov_b32_e32 v89, v133
	v_mov_b32_e32 v90, v133
	v_mov_b32_e32 v91, v133
	v_mov_b32_e32 v92, v133
	v_mov_b32_e32 v93, v133
	v_mov_b32_e32 v94, v133
	v_mov_b32_e32 v95, v133
	v_mov_b32_e32 v104, v133
	v_mov_b32_e32 v105, v133
	v_mov_b32_e32 v106, v133
	v_mov_b32_e32 v107, v133
	v_mov_b32_e32 v108, v133
	v_mov_b32_e32 v109, v133
	v_mov_b32_e32 v110, v133
	v_mov_b32_e32 v111, v133
	v_mov_b32_e32 v120, v133
	v_mov_b32_e32 v121, v133
	v_mov_b32_e32 v122, v133
	v_mov_b32_e32 v123, v133
	v_mov_b32_e32 v124, v133
	v_mov_b32_e32 v125, v133
	v_mov_b32_e32 v126, v133
	v_mov_b32_e32 v127, v133
	s_barrier
	.p2align 6

.LBB0_2507:
	s_add_i32 s15, s1, -2
	s_add_u32 s26, s26, 0x40080
	s_addc_u32 s27, s27, 0
	s_add_u32 s17, s28, 0x100
	v_mov_b32_e32 v0, 0
	s_addc_u32 s19, s29, 0
	s_mov_b32 s23, 0
	v_mov_b32_e32 v1, v0
	v_mov_b32_e32 v2, v0
	v_mov_b32_e32 v3, v0
	v_mov_b32_e32 v4, v0
	v_mov_b32_e32 v5, v0
	v_mov_b32_e32 v6, v0
	v_mov_b32_e32 v7, v0
	v_mov_b32_e32 v8, v0
	v_mov_b32_e32 v9, v0
	v_mov_b32_e32 v10, v0
	v_mov_b32_e32 v11, v0
	v_mov_b32_e32 v12, v0
	v_mov_b32_e32 v13, v0
	v_mov_b32_e32 v14, v0
	v_mov_b32_e32 v15, v0
	v_mov_b32_e32 v24, v0
	v_mov_b32_e32 v25, v0
	v_mov_b32_e32 v26, v0
	v_mov_b32_e32 v27, v0
	v_mov_b32_e32 v28, v0
	v_mov_b32_e32 v29, v0
	v_mov_b32_e32 v30, v0
	v_mov_b32_e32 v31, v0
	v_mov_b32_e32 v40, v0
	v_mov_b32_e32 v41, v0
	v_mov_b32_e32 v42, v0
	v_mov_b32_e32 v43, v0
	v_mov_b32_e32 v44, v0
	v_mov_b32_e32 v45, v0
	v_mov_b32_e32 v46, v0
	v_mov_b32_e32 v47, v0
	v_mov_b32_e32 v16, v0
	v_mov_b32_e32 v17, v0
	v_mov_b32_e32 v18, v0
	v_mov_b32_e32 v19, v0
	v_mov_b32_e32 v20, v0
	v_mov_b32_e32 v21, v0
	v_mov_b32_e32 v22, v0
	v_mov_b32_e32 v23, v0
	v_mov_b32_e32 v32, v0
	v_mov_b32_e32 v33, v0
	v_mov_b32_e32 v34, v0
	v_mov_b32_e32 v35, v0
	v_mov_b32_e32 v36, v0
	v_mov_b32_e32 v37, v0
	v_mov_b32_e32 v38, v0
	v_mov_b32_e32 v39, v0
	v_mov_b32_e32 v48, v0
	v_mov_b32_e32 v49, v0
	v_mov_b32_e32 v50, v0
	v_mov_b32_e32 v51, v0
	v_mov_b32_e32 v52, v0
	v_mov_b32_e32 v53, v0
	v_mov_b32_e32 v54, v0
	v_mov_b32_e32 v55, v0
	v_mov_b32_e32 v56, v0
	v_mov_b32_e32 v57, v0
	v_mov_b32_e32 v58, v0
	v_mov_b32_e32 v59, v0
	v_mov_b32_e32 v60, v0
	v_mov_b32_e32 v61, v0
	v_mov_b32_e32 v62, v0
	v_mov_b32_e32 v63, v0
	v_mov_b32_e32 v64, v0
	v_mov_b32_e32 v65, v0
	v_mov_b32_e32 v66, v0
	v_mov_b32_e32 v67, v0
	v_mov_b32_e32 v68, v0
	v_mov_b32_e32 v69, v0
	v_mov_b32_e32 v70, v0
	v_mov_b32_e32 v71, v0
	v_mov_b32_e32 v72, v0
	v_mov_b32_e32 v73, v0
	v_mov_b32_e32 v74, v0
	v_mov_b32_e32 v75, v0
	v_mov_b32_e32 v76, v0
	v_mov_b32_e32 v77, v0
	v_mov_b32_e32 v78, v0
	v_mov_b32_e32 v79, v0
	v_mov_b32_e32 v88, v0
	v_mov_b32_e32 v89, v0
	v_mov_b32_e32 v90, v0
	v_mov_b32_e32 v91, v0
	v_mov_b32_e32 v92, v0
	v_mov_b32_e32 v93, v0
	v_mov_b32_e32 v94, v0
	v_mov_b32_e32 v95, v0
	v_mov_b32_e32 v104, v0
	v_mov_b32_e32 v105, v0
	v_mov_b32_e32 v106, v0
	v_mov_b32_e32 v107, v0
	v_mov_b32_e32 v108, v0
	v_mov_b32_e32 v109, v0
	v_mov_b32_e32 v110, v0
	v_mov_b32_e32 v111, v0
	v_mov_b32_e32 v80, v0
	v_mov_b32_e32 v81, v0
	v_mov_b32_e32 v82, v0
	v_mov_b32_e32 v83, v0
	v_mov_b32_e32 v84, v0
	v_mov_b32_e32 v85, v0
	v_mov_b32_e32 v86, v0
	v_mov_b32_e32 v87, v0
	v_mov_b32_e32 v96, v0
	v_mov_b32_e32 v97, v0
	v_mov_b32_e32 v98, v0
	v_mov_b32_e32 v99, v0
	v_mov_b32_e32 v100, v0
	v_mov_b32_e32 v101, v0
	v_mov_b32_e32 v102, v0
	v_mov_b32_e32 v103, v0
	v_mov_b32_e32 v112, v0
	v_mov_b32_e32 v113, v0
	v_mov_b32_e32 v114, v0
	v_mov_b32_e32 v115, v0
	v_mov_b32_e32 v116, v0
	v_mov_b32_e32 v117, v0
	v_mov_b32_e32 v118, v0
	v_mov_b32_e32 v119, v0
	v_mov_b32_e32 v120, v0
	v_mov_b32_e32 v121, v0
	v_mov_b32_e32 v122, v0
	v_mov_b32_e32 v123, v0
	v_mov_b32_e32 v124, v0
	v_mov_b32_e32 v125, v0
	v_mov_b32_e32 v126, v0
	v_mov_b32_e32 v127, v0
	.p2align 6

.LBB0_2662:
	s_ashr_i32 s37, s36, 31
	s_lshl_b64 s[40:41], s[36:37], 19
	s_add_u32 s40, s86, s40
	s_addc_u32 s41, s87, s41
	s_and_b64 s[42:43], s[6:7], exec
	s_cselect_b32 s17, s41, s45
	s_cselect_b32 s19, s40, s44
	s_ashr_i32 s39, s38, 31
	s_lshl_b64 s[42:43], s[38:39], 19
	v_readlane_b32 s48, v235, 26
	v_readlane_b32 s49, v235, 27
	s_add_u32 s42, s48, s42
	s_addc_u32 s43, s49, s43
	s_and_b64 s[48:49], s[6:7], exec
	s_cselect_b32 s37, s43, s47
	s_cselect_b32 s39, s42, s46
	s_add_u32 s67, s46, 0x100
	v_mov_b32_e32 v4, 0
	s_addc_u32 s68, s47, 0
	s_mov_b32 s69, -2
	v_mov_b32_e32 v5, v4
	v_mov_b32_e32 v6, v4
	v_mov_b32_e32 v7, v4
	v_mov_b32_e32 v0, v4
	v_mov_b32_e32 v1, v4
	v_mov_b32_e32 v2, v4
	v_mov_b32_e32 v3, v4
	v_mov_b32_e32 v28, v4
	v_mov_b32_e32 v29, v4
	v_mov_b32_e32 v30, v4
	v_mov_b32_e32 v31, v4
	v_mov_b32_e32 v20, v4
	v_mov_b32_e32 v21, v4
	v_mov_b32_e32 v22, v4
	v_mov_b32_e32 v23, v4
	v_mov_b32_e32 v24, v4
	v_mov_b32_e32 v25, v4
	v_mov_b32_e32 v26, v4
	v_mov_b32_e32 v27, v4
	v_mov_b32_e32 v32, v4
	v_mov_b32_e32 v33, v4
	v_mov_b32_e32 v34, v4
	v_mov_b32_e32 v35, v4
	v_mov_b32_e32 v44, v4
	v_mov_b32_e32 v45, v4
	v_mov_b32_e32 v46, v4
	v_mov_b32_e32 v47, v4
	v_mov_b32_e32 v40, v4
	v_mov_b32_e32 v41, v4
	v_mov_b32_e32 v42, v4
	v_mov_b32_e32 v43, v4
	v_mov_b32_e32 v12, v4
	v_mov_b32_e32 v13, v4
	v_mov_b32_e32 v14, v4
	v_mov_b32_e32 v15, v4
	v_mov_b32_e32 v8, v4
	v_mov_b32_e32 v9, v4
	v_mov_b32_e32 v10, v4
	v_mov_b32_e32 v11, v4
	v_mov_b32_e32 v128, v4
	v_mov_b32_e32 v129, v4
	v_mov_b32_e32 v130, v4
	v_mov_b32_e32 v131, v4
	v_mov_b32_e32 v132, v4
	v_mov_b32_e32 v133, v4
	v_mov_b32_e32 v134, v4
	v_mov_b32_e32 v135, v4
	v_mov_b32_e32 v48, v4
	v_mov_b32_e32 v49, v4
	v_mov_b32_e32 v50, v4
	v_mov_b32_e32 v51, v4
	v_mov_b32_e32 v52, v4
	v_mov_b32_e32 v53, v4
	v_mov_b32_e32 v54, v4
	v_mov_b32_e32 v55, v4
	v_mov_b32_e32 v36, v4
	v_mov_b32_e32 v37, v4
	v_mov_b32_e32 v38, v4
	v_mov_b32_e32 v39, v4
	v_mov_b32_e32 v16, v4
	v_mov_b32_e32 v17, v4
	v_mov_b32_e32 v18, v4
	v_mov_b32_e32 v19, v4
	v_mov_b32_e32 v56, v4
	v_mov_b32_e32 v57, v4
	v_mov_b32_e32 v58, v4
	v_mov_b32_e32 v59, v4
	v_mov_b32_e32 v60, v4
	v_mov_b32_e32 v61, v4
	v_mov_b32_e32 v62, v4
	v_mov_b32_e32 v63, v4
	v_mov_b32_e32 v64, v4
	v_mov_b32_e32 v65, v4
	v_mov_b32_e32 v66, v4
	v_mov_b32_e32 v67, v4
	v_mov_b32_e32 v68, v4
	v_mov_b32_e32 v69, v4
	v_mov_b32_e32 v70, v4
	v_mov_b32_e32 v71, v4
	v_mov_b32_e32 v72, v4
	v_mov_b32_e32 v73, v4
	v_mov_b32_e32 v74, v4
	v_mov_b32_e32 v75, v4
	v_mov_b32_e32 v76, v4
	v_mov_b32_e32 v77, v4
	v_mov_b32_e32 v78, v4
	v_mov_b32_e32 v79, v4
	v_mov_b32_e32 v80, v4
	v_mov_b32_e32 v81, v4
	v_mov_b32_e32 v82, v4
	v_mov_b32_e32 v83, v4
	v_mov_b32_e32 v88, v4
	v_mov_b32_e32 v89, v4
	v_mov_b32_e32 v90, v4
	v_mov_b32_e32 v91, v4
	v_mov_b32_e32 v136, v4
	v_mov_b32_e32 v137, v4
	v_mov_b32_e32 v138, v4
	v_mov_b32_e32 v139, v4
	v_mov_b32_e32 v140, v4
	v_mov_b32_e32 v141, v4
	v_mov_b32_e32 v142, v4
	v_mov_b32_e32 v143, v4
	v_mov_b32_e32 v84, v4
	v_mov_b32_e32 v85, v4
	v_mov_b32_e32 v86, v4
	v_mov_b32_e32 v87, v4
	v_mov_b32_e32 v92, v4
	v_mov_b32_e32 v93, v4
	v_mov_b32_e32 v94, v4
	v_mov_b32_e32 v95, v4
	v_mov_b32_e32 v116, v4
	v_mov_b32_e32 v117, v4
	v_mov_b32_e32 v118, v4
	v_mov_b32_e32 v119, v4
	v_mov_b32_e32 v112, v4
	v_mov_b32_e32 v113, v4
	v_mov_b32_e32 v114, v4
	v_mov_b32_e32 v115, v4
	v_mov_b32_e32 v100, v4
	v_mov_b32_e32 v101, v4
	v_mov_b32_e32 v102, v4
	v_mov_b32_e32 v103, v4
	v_mov_b32_e32 v96, v4
	v_mov_b32_e32 v97, v4
	v_mov_b32_e32 v98, v4
	v_mov_b32_e32 v99, v4
	.p2align 6

.LBB0_2783:
	s_add_i32 s35, s72, -2
	s_add_u32 s73, s40, 0x100
	v_mov_b32_e32 v0, 0
	s_addc_u32 s80, s41, 0
	s_mov_b32 s42, 0
	v_mov_b32_e32 v1, v0
	v_mov_b32_e32 v2, v0
	v_mov_b32_e32 v3, v0
	v_mov_b32_e32 v4, v0
	v_mov_b32_e32 v5, v0
	v_mov_b32_e32 v6, v0
	v_mov_b32_e32 v7, v0
	v_mov_b32_e32 v8, v0
	v_mov_b32_e32 v9, v0
	v_mov_b32_e32 v10, v0
	v_mov_b32_e32 v11, v0
	v_mov_b32_e32 v12, v0
	v_mov_b32_e32 v13, v0
	v_mov_b32_e32 v14, v0
	v_mov_b32_e32 v15, v0
	v_mov_b32_e32 v20, v0
	v_mov_b32_e32 v21, v0
	v_mov_b32_e32 v22, v0
	v_mov_b32_e32 v23, v0
	v_mov_b32_e32 v28, v0
	v_mov_b32_e32 v29, v0
	v_mov_b32_e32 v30, v0
	v_mov_b32_e32 v31, v0
	v_mov_b32_e32 v36, v0
	v_mov_b32_e32 v37, v0
	v_mov_b32_e32 v38, v0
	v_mov_b32_e32 v39, v0
	v_mov_b32_e32 v44, v0
	v_mov_b32_e32 v45, v0
	v_mov_b32_e32 v46, v0
	v_mov_b32_e32 v47, v0
	v_mov_b32_e32 v16, v0
	v_mov_b32_e32 v17, v0
	v_mov_b32_e32 v18, v0
	v_mov_b32_e32 v19, v0
	v_mov_b32_e32 v24, v0
	v_mov_b32_e32 v25, v0
	v_mov_b32_e32 v26, v0
	v_mov_b32_e32 v27, v0
	v_mov_b32_e32 v32, v0
	v_mov_b32_e32 v33, v0
	v_mov_b32_e32 v34, v0
	v_mov_b32_e32 v35, v0
	v_mov_b32_e32 v40, v0
	v_mov_b32_e32 v41, v0
	v_mov_b32_e32 v42, v0
	v_mov_b32_e32 v43, v0
	v_mov_b32_e32 v48, v0
	v_mov_b32_e32 v49, v0
	v_mov_b32_e32 v50, v0
	v_mov_b32_e32 v51, v0
	v_mov_b32_e32 v52, v0
	v_mov_b32_e32 v53, v0
	v_mov_b32_e32 v54, v0
	v_mov_b32_e32 v55, v0
	v_mov_b32_e32 v56, v0
	v_mov_b32_e32 v57, v0
	v_mov_b32_e32 v58, v0
	v_mov_b32_e32 v59, v0
	v_mov_b32_e32 v60, v0
	v_mov_b32_e32 v61, v0
	v_mov_b32_e32 v62, v0
	v_mov_b32_e32 v63, v0
	v_mov_b32_e32 v64, v0
	v_mov_b32_e32 v65, v0
	v_mov_b32_e32 v66, v0
	v_mov_b32_e32 v67, v0
	v_mov_b32_e32 v68, v0
	v_mov_b32_e32 v69, v0
	v_mov_b32_e32 v70, v0
	v_mov_b32_e32 v71, v0
	v_mov_b32_e32 v72, v0
	v_mov_b32_e32 v73, v0
	v_mov_b32_e32 v74, v0
	v_mov_b32_e32 v75, v0
	v_mov_b32_e32 v76, v0
	v_mov_b32_e32 v77, v0
	v_mov_b32_e32 v78, v0
	v_mov_b32_e32 v79, v0
	v_mov_b32_e32 v84, v0
	v_mov_b32_e32 v85, v0
	v_mov_b32_e32 v86, v0
	v_mov_b32_e32 v87, v0
	v_mov_b32_e32 v92, v0
	v_mov_b32_e32 v93, v0
	v_mov_b32_e32 v94, v0
	v_mov_b32_e32 v95, v0
	v_mov_b32_e32 v100, v0
	v_mov_b32_e32 v101, v0
	v_mov_b32_e32 v102, v0
	v_mov_b32_e32 v103, v0
	v_mov_b32_e32 v108, v0
	v_mov_b32_e32 v109, v0
	v_mov_b32_e32 v110, v0
	v_mov_b32_e32 v111, v0
	v_mov_b32_e32 v80, v0
	v_mov_b32_e32 v81, v0
	v_mov_b32_e32 v82, v0
	v_mov_b32_e32 v83, v0
	v_mov_b32_e32 v88, v0
	v_mov_b32_e32 v89, v0
	v_mov_b32_e32 v90, v0
	v_mov_b32_e32 v91, v0
	v_mov_b32_e32 v96, v0
	v_mov_b32_e32 v97, v0
	v_mov_b32_e32 v98, v0
	v_mov_b32_e32 v99, v0
	v_mov_b32_e32 v104, v0
	v_mov_b32_e32 v105, v0
	v_mov_b32_e32 v106, v0
	v_mov_b32_e32 v107, v0
	v_mov_b32_e32 v112, v0
	v_mov_b32_e32 v113, v0
	v_mov_b32_e32 v114, v0
	v_mov_b32_e32 v115, v0
	v_mov_b32_e32 v116, v0
	v_mov_b32_e32 v117, v0
	v_mov_b32_e32 v118, v0
	v_mov_b32_e32 v119, v0
	v_mov_b32_e32 v120, v0
	v_mov_b32_e32 v121, v0
	v_mov_b32_e32 v122, v0
	v_mov_b32_e32 v123, v0
	v_mov_b32_e32 v124, v0
	v_mov_b32_e32 v125, v0
	v_mov_b32_e32 v126, v0
	v_mov_b32_e32 v127, v0
	.p2align 6
